# row LayerNorm phases 9 and 15 rewritten by hand: 4 rows per wave in flight with next rows prefetched, gamma/beta in registers, interleaved wave reductions
# speedup vs baseline: 1.0238x; 1.0238x over previous
.LBB0_553:
	s_add_u32 s64, s68, 0xf200000
	s_addc_u32 s65, s69, 0
	s_cmp_lt_i32 s70, 10
	s_cselect_b64 s[0:1], -1, 0
	s_cmp_gt_i32 s71, 9
	s_cselect_b64 s[2:3], -1, 0
	s_and_b64 s[0:1], s[0:1], s[2:3]
	s_andn2_b64 vcc, exec, s[0:1]
	s_cbranch_vccnz .LBB0_570
	v_readlane_b32 s8, v254, 18
	v_readlane_b32 s9, v254, 19
	s_nop 4
	s_cmp_lt_i32 s94, 0x8000
	s_cbranch_scc0 .Llnh_done
	v_lshlrev_b32_e32 v0, 4, v184
	v_lshlrev_b32_e32 v1, 5, v184
	v_xor_b32_e32 v2, 1, v184
	v_lshlrev_b32_e32 v2, 2, v2
	v_xor_b32_e32 v3, 2, v184
	v_lshlrev_b32_e32 v3, 2, v3
	v_xor_b32_e32 v4, 4, v184
	v_lshlrev_b32_e32 v4, 2, v4
	v_xor_b32_e32 v5, 8, v184
	v_lshlrev_b32_e32 v5, 2, v5
	v_xor_b32_e32 v6, 16, v184
	v_lshlrev_b32_e32 v6, 2, v6
	v_xor_b32_e32 v7, 32, v184
	v_lshlrev_b32_e32 v7, 2, v7
	v_mov_b32_e32 v8, 0x3727c5ac
	global_load_dwordx4 v[16:19], v1, s[82:83]
	global_load_dwordx4 v[20:23], v1, s[82:83] offset:16
	global_load_dwordx4 v[24:27], v1, s[82:83] offset:2048
	global_load_dwordx4 v[28:31], v1, s[82:83] offset:2064
	global_load_dwordx4 v[32:35], v1, s[8:9]
	global_load_dwordx4 v[36:39], v1, s[8:9] offset:16
	global_load_dwordx4 v[40:43], v1, s[8:9] offset:2048
	global_load_dwordx4 v[44:47], v1, s[8:9] offset:2064
	s_mov_b32 s0, s94
	s_lshl_b32 s14, s46, 2
	s_mov_b32 s5, s0
	s_lshl_b32 s4, s5, 11
	s_add_u32 s2, s88, s4
	s_addc_u32 s3, s89, 0
	global_load_dwordx4 v[48:51], v0, s[2:3] nt
	global_load_dwordx4 v[52:55], v0, s[2:3] offset:1024 nt
	s_mov_b32 s4, s46
	s_add_i32 s5, s0, s4
	s_cmp_lt_i32 s5, 0x8000
	s_cselect_b32 s5, s5, s0
	s_lshl_b32 s4, s5, 11
	s_add_u32 s2, s88, s4
	s_addc_u32 s3, s89, 0
	global_load_dwordx4 v[56:59], v0, s[2:3] nt
	global_load_dwordx4 v[60:63], v0, s[2:3] offset:1024 nt
	s_mul_i32 s4, s46, 2
	s_add_i32 s5, s0, s4
	s_cmp_lt_i32 s5, 0x8000
	s_cselect_b32 s5, s5, s0
	s_lshl_b32 s4, s5, 11
	s_add_u32 s2, s88, s4
	s_addc_u32 s3, s89, 0
	global_load_dwordx4 v[64:67], v0, s[2:3] nt
	global_load_dwordx4 v[68:71], v0, s[2:3] offset:1024 nt
	s_mul_i32 s4, s46, 3
	s_add_i32 s5, s0, s4
	s_cmp_lt_i32 s5, 0x8000
	s_cselect_b32 s5, s5, s0
	s_lshl_b32 s4, s5, 11
	s_add_u32 s2, s88, s4
	s_addc_u32 s3, s89, 0
	global_load_dwordx4 v[72:75], v0, s[2:3] nt
	global_load_dwordx4 v[76:79], v0, s[2:3] offset:1024 nt
.Llnh_top:
	s_waitcnt vmcnt(0)
	v_lshlrev_b32_e32 v112, 16, v48
	v_and_b32_e32 v113, 0xffff0000, v48
	v_lshlrev_b32_e32 v128, 16, v56
	v_and_b32_e32 v129, 0xffff0000, v56
	v_lshlrev_b32_e32 v144, 16, v64
	v_and_b32_e32 v145, 0xffff0000, v64
	v_lshlrev_b32_e32 v160, 16, v72
	v_and_b32_e32 v161, 0xffff0000, v72
	v_lshlrev_b32_e32 v114, 16, v49
	v_and_b32_e32 v115, 0xffff0000, v49
	v_lshlrev_b32_e32 v130, 16, v57
	v_and_b32_e32 v131, 0xffff0000, v57
	v_lshlrev_b32_e32 v146, 16, v65
	v_and_b32_e32 v147, 0xffff0000, v65
	v_lshlrev_b32_e32 v162, 16, v73
	v_and_b32_e32 v163, 0xffff0000, v73
	v_lshlrev_b32_e32 v116, 16, v50
	v_and_b32_e32 v117, 0xffff0000, v50
	v_lshlrev_b32_e32 v132, 16, v58
	v_and_b32_e32 v133, 0xffff0000, v58
	v_lshlrev_b32_e32 v148, 16, v66
	v_and_b32_e32 v149, 0xffff0000, v66
	v_lshlrev_b32_e32 v164, 16, v74
	v_and_b32_e32 v165, 0xffff0000, v74
	v_lshlrev_b32_e32 v118, 16, v51
	v_and_b32_e32 v119, 0xffff0000, v51
	v_lshlrev_b32_e32 v134, 16, v59
	v_and_b32_e32 v135, 0xffff0000, v59
	v_lshlrev_b32_e32 v150, 16, v67
	v_and_b32_e32 v151, 0xffff0000, v67
	v_lshlrev_b32_e32 v166, 16, v75
	v_and_b32_e32 v167, 0xffff0000, v75
	v_lshlrev_b32_e32 v120, 16, v52
	v_and_b32_e32 v121, 0xffff0000, v52
	v_lshlrev_b32_e32 v136, 16, v60
	v_and_b32_e32 v137, 0xffff0000, v60
	v_lshlrev_b32_e32 v152, 16, v68
	v_and_b32_e32 v153, 0xffff0000, v68
	v_lshlrev_b32_e32 v168, 16, v76
	v_and_b32_e32 v169, 0xffff0000, v76
	v_lshlrev_b32_e32 v122, 16, v53
	v_and_b32_e32 v123, 0xffff0000, v53
	v_lshlrev_b32_e32 v138, 16, v61
	v_and_b32_e32 v139, 0xffff0000, v61
	v_lshlrev_b32_e32 v154, 16, v69
	v_and_b32_e32 v155, 0xffff0000, v69
	v_lshlrev_b32_e32 v170, 16, v77
	v_and_b32_e32 v171, 0xffff0000, v77
	v_lshlrev_b32_e32 v124, 16, v54
	v_and_b32_e32 v125, 0xffff0000, v54
	v_lshlrev_b32_e32 v140, 16, v62
	v_and_b32_e32 v141, 0xffff0000, v62
	v_lshlrev_b32_e32 v156, 16, v70
	v_and_b32_e32 v157, 0xffff0000, v70
	v_lshlrev_b32_e32 v172, 16, v78
	v_and_b32_e32 v173, 0xffff0000, v78
	v_lshlrev_b32_e32 v126, 16, v55
	v_and_b32_e32 v127, 0xffff0000, v55
	v_lshlrev_b32_e32 v142, 16, v63
	v_and_b32_e32 v143, 0xffff0000, v63
	v_lshlrev_b32_e32 v158, 16, v71
	v_and_b32_e32 v159, 0xffff0000, v71
	v_lshlrev_b32_e32 v174, 16, v79
	v_and_b32_e32 v175, 0xffff0000, v79
	v_add_f32_e32 v176, v112, v113
	v_add_f32_e32 v178, v128, v129
	v_add_f32_e32 v180, v144, v145
	v_add_f32_e32 v182, v160, v161
	v_add_f32_e32 v176, v176, v114
	v_add_f32_e32 v178, v178, v130
	v_add_f32_e32 v180, v180, v146
	v_add_f32_e32 v182, v182, v162
	v_add_f32_e32 v176, v176, v115
	v_add_f32_e32 v178, v178, v131
	v_add_f32_e32 v180, v180, v147
	v_add_f32_e32 v182, v182, v163
	v_add_f32_e32 v176, v176, v116
	v_add_f32_e32 v178, v178, v132
	v_add_f32_e32 v180, v180, v148
	v_add_f32_e32 v182, v182, v164
	v_add_f32_e32 v176, v176, v117
	v_add_f32_e32 v178, v178, v133
	v_add_f32_e32 v180, v180, v149
	v_add_f32_e32 v182, v182, v165
	v_add_f32_e32 v176, v176, v118
	v_add_f32_e32 v178, v178, v134
	v_add_f32_e32 v180, v180, v150
	v_add_f32_e32 v182, v182, v166
	v_add_f32_e32 v176, v176, v119
	v_add_f32_e32 v178, v178, v135
	v_add_f32_e32 v180, v180, v151
	v_add_f32_e32 v182, v182, v167
	v_add_f32_e32 v176, v176, v120
	v_add_f32_e32 v178, v178, v136
	v_add_f32_e32 v180, v180, v152
	v_add_f32_e32 v182, v182, v168
	v_add_f32_e32 v176, v176, v121
	v_add_f32_e32 v178, v178, v137
	v_add_f32_e32 v180, v180, v153
	v_add_f32_e32 v182, v182, v169
	v_add_f32_e32 v176, v176, v122
	v_add_f32_e32 v178, v178, v138
	v_add_f32_e32 v180, v180, v154
	v_add_f32_e32 v182, v182, v170
	v_add_f32_e32 v176, v176, v123
	v_add_f32_e32 v178, v178, v139
	v_add_f32_e32 v180, v180, v155
	v_add_f32_e32 v182, v182, v171
	v_add_f32_e32 v176, v176, v124
	v_add_f32_e32 v178, v178, v140
	v_add_f32_e32 v180, v180, v156
	v_add_f32_e32 v182, v182, v172
	v_add_f32_e32 v176, v176, v125
	v_add_f32_e32 v178, v178, v141
	v_add_f32_e32 v180, v180, v157
	v_add_f32_e32 v182, v182, v173
	v_add_f32_e32 v176, v176, v126
	v_add_f32_e32 v178, v178, v142
	v_add_f32_e32 v180, v180, v158
	v_add_f32_e32 v182, v182, v174
	v_add_f32_e32 v176, v176, v127
	v_add_f32_e32 v178, v178, v143
	v_add_f32_e32 v180, v180, v159
	v_add_f32_e32 v182, v182, v175
	s_add_i32 s1, s0, s14
	s_cmp_lt_i32 s1, 0x8000
	s_cbranch_scc0 .Llnh_np1
	s_mov_b32 s5, s1
	s_lshl_b32 s4, s5, 11
	s_add_u32 s2, s88, s4
	s_addc_u32 s3, s89, 0
	global_load_dwordx4 v[80:83], v0, s[2:3] nt
	global_load_dwordx4 v[84:87], v0, s[2:3] offset:1024 nt
	s_mov_b32 s4, s46
	s_add_i32 s5, s1, s4
	s_cmp_lt_i32 s5, 0x8000
	s_cselect_b32 s5, s5, s1
	s_lshl_b32 s4, s5, 11
	s_add_u32 s2, s88, s4
	s_addc_u32 s3, s89, 0
	global_load_dwordx4 v[88:91], v0, s[2:3] nt
	global_load_dwordx4 v[92:95], v0, s[2:3] offset:1024 nt
	s_mul_i32 s4, s46, 2
	s_add_i32 s5, s1, s4
	s_cmp_lt_i32 s5, 0x8000
	s_cselect_b32 s5, s5, s1
	s_lshl_b32 s4, s5, 11
	s_add_u32 s2, s88, s4
	s_addc_u32 s3, s89, 0
	global_load_dwordx4 v[96:99], v0, s[2:3] nt
	global_load_dwordx4 v[100:103], v0, s[2:3] offset:1024 nt
	s_mul_i32 s4, s46, 3
	s_add_i32 s5, s1, s4
	s_cmp_lt_i32 s5, 0x8000
	s_cselect_b32 s5, s5, s1
	s_lshl_b32 s4, s5, 11
	s_add_u32 s2, s88, s4
	s_addc_u32 s3, s89, 0
	global_load_dwordx4 v[104:107], v0, s[2:3] nt
	global_load_dwordx4 v[108:111], v0, s[2:3] offset:1024 nt
.Llnh_np1:
	ds_bpermute_b32 v188, v2, v176
	ds_bpermute_b32 v189, v2, v178
	ds_bpermute_b32 v190, v2, v180
	ds_bpermute_b32 v191, v2, v182
	s_waitcnt lgkmcnt(0)
	v_add_f32_e32 v176, v176, v188
	v_add_f32_e32 v178, v178, v189
	v_add_f32_e32 v180, v180, v190
	v_add_f32_e32 v182, v182, v191
	ds_bpermute_b32 v188, v3, v176
	ds_bpermute_b32 v189, v3, v178
	ds_bpermute_b32 v190, v3, v180
	ds_bpermute_b32 v191, v3, v182
	s_waitcnt lgkmcnt(0)
	v_add_f32_e32 v176, v176, v188
	v_add_f32_e32 v178, v178, v189
	v_add_f32_e32 v180, v180, v190
	v_add_f32_e32 v182, v182, v191
	ds_bpermute_b32 v188, v4, v176
	ds_bpermute_b32 v189, v4, v178
	ds_bpermute_b32 v190, v4, v180
	ds_bpermute_b32 v191, v4, v182
	s_waitcnt lgkmcnt(0)
	v_add_f32_e32 v176, v176, v188
	v_add_f32_e32 v178, v178, v189
	v_add_f32_e32 v180, v180, v190
	v_add_f32_e32 v182, v182, v191
	ds_bpermute_b32 v188, v5, v176
	ds_bpermute_b32 v189, v5, v178
	ds_bpermute_b32 v190, v5, v180
	ds_bpermute_b32 v191, v5, v182
	s_waitcnt lgkmcnt(0)
	v_add_f32_e32 v176, v176, v188
	v_add_f32_e32 v178, v178, v189
	v_add_f32_e32 v180, v180, v190
	v_add_f32_e32 v182, v182, v191
	ds_bpermute_b32 v188, v6, v176
	ds_bpermute_b32 v189, v6, v178
	ds_bpermute_b32 v190, v6, v180
	ds_bpermute_b32 v191, v6, v182
	s_waitcnt lgkmcnt(0)
	v_add_f32_e32 v176, v176, v188
	v_add_f32_e32 v178, v178, v189
	v_add_f32_e32 v180, v180, v190
	v_add_f32_e32 v182, v182, v191
	ds_bpermute_b32 v188, v7, v176
	ds_bpermute_b32 v189, v7, v178
	ds_bpermute_b32 v190, v7, v180
	ds_bpermute_b32 v191, v7, v182
	s_waitcnt lgkmcnt(0)
	v_add_f32_e32 v176, v176, v188
	v_add_f32_e32 v178, v178, v189
	v_add_f32_e32 v180, v180, v190
	v_add_f32_e32 v182, v182, v191
	v_mul_f32_e32 v176, 0x3a800000, v176
	v_mul_f32_e32 v178, 0x3a800000, v178
	v_mul_f32_e32 v180, 0x3a800000, v180
	v_mul_f32_e32 v182, 0x3a800000, v182
	v_pk_add_f32 v[112:113], v[112:113], v[176:177] op_sel_hi:[1,0] neg_lo:[0,1] neg_hi:[0,1]
	v_pk_add_f32 v[128:129], v[128:129], v[178:179] op_sel_hi:[1,0] neg_lo:[0,1] neg_hi:[0,1]
	v_pk_add_f32 v[144:145], v[144:145], v[180:181] op_sel_hi:[1,0] neg_lo:[0,1] neg_hi:[0,1]
	v_pk_add_f32 v[160:161], v[160:161], v[182:183] op_sel_hi:[1,0] neg_lo:[0,1] neg_hi:[0,1]
	v_pk_add_f32 v[114:115], v[114:115], v[176:177] op_sel_hi:[1,0] neg_lo:[0,1] neg_hi:[0,1]
	v_pk_add_f32 v[130:131], v[130:131], v[178:179] op_sel_hi:[1,0] neg_lo:[0,1] neg_hi:[0,1]
	v_pk_add_f32 v[146:147], v[146:147], v[180:181] op_sel_hi:[1,0] neg_lo:[0,1] neg_hi:[0,1]
	v_pk_add_f32 v[162:163], v[162:163], v[182:183] op_sel_hi:[1,0] neg_lo:[0,1] neg_hi:[0,1]
	v_pk_add_f32 v[116:117], v[116:117], v[176:177] op_sel_hi:[1,0] neg_lo:[0,1] neg_hi:[0,1]
	v_pk_add_f32 v[132:133], v[132:133], v[178:179] op_sel_hi:[1,0] neg_lo:[0,1] neg_hi:[0,1]
	v_pk_add_f32 v[148:149], v[148:149], v[180:181] op_sel_hi:[1,0] neg_lo:[0,1] neg_hi:[0,1]
	v_pk_add_f32 v[164:165], v[164:165], v[182:183] op_sel_hi:[1,0] neg_lo:[0,1] neg_hi:[0,1]
	v_pk_add_f32 v[118:119], v[118:119], v[176:177] op_sel_hi:[1,0] neg_lo:[0,1] neg_hi:[0,1]
	v_pk_add_f32 v[134:135], v[134:135], v[178:179] op_sel_hi:[1,0] neg_lo:[0,1] neg_hi:[0,1]
	v_pk_add_f32 v[150:151], v[150:151], v[180:181] op_sel_hi:[1,0] neg_lo:[0,1] neg_hi:[0,1]
	v_pk_add_f32 v[166:167], v[166:167], v[182:183] op_sel_hi:[1,0] neg_lo:[0,1] neg_hi:[0,1]
	v_pk_add_f32 v[120:121], v[120:121], v[176:177] op_sel_hi:[1,0] neg_lo:[0,1] neg_hi:[0,1]
	v_pk_add_f32 v[136:137], v[136:137], v[178:179] op_sel_hi:[1,0] neg_lo:[0,1] neg_hi:[0,1]
	v_pk_add_f32 v[152:153], v[152:153], v[180:181] op_sel_hi:[1,0] neg_lo:[0,1] neg_hi:[0,1]
	v_pk_add_f32 v[168:169], v[168:169], v[182:183] op_sel_hi:[1,0] neg_lo:[0,1] neg_hi:[0,1]
	v_pk_add_f32 v[122:123], v[122:123], v[176:177] op_sel_hi:[1,0] neg_lo:[0,1] neg_hi:[0,1]
	v_pk_add_f32 v[138:139], v[138:139], v[178:179] op_sel_hi:[1,0] neg_lo:[0,1] neg_hi:[0,1]
	v_pk_add_f32 v[154:155], v[154:155], v[180:181] op_sel_hi:[1,0] neg_lo:[0,1] neg_hi:[0,1]
	v_pk_add_f32 v[170:171], v[170:171], v[182:183] op_sel_hi:[1,0] neg_lo:[0,1] neg_hi:[0,1]
	v_pk_add_f32 v[124:125], v[124:125], v[176:177] op_sel_hi:[1,0] neg_lo:[0,1] neg_hi:[0,1]
	v_pk_add_f32 v[140:141], v[140:141], v[178:179] op_sel_hi:[1,0] neg_lo:[0,1] neg_hi:[0,1]
	v_pk_add_f32 v[156:157], v[156:157], v[180:181] op_sel_hi:[1,0] neg_lo:[0,1] neg_hi:[0,1]
	v_pk_add_f32 v[172:173], v[172:173], v[182:183] op_sel_hi:[1,0] neg_lo:[0,1] neg_hi:[0,1]
	v_pk_add_f32 v[126:127], v[126:127], v[176:177] op_sel_hi:[1,0] neg_lo:[0,1] neg_hi:[0,1]
	v_pk_add_f32 v[142:143], v[142:143], v[178:179] op_sel_hi:[1,0] neg_lo:[0,1] neg_hi:[0,1]
	v_pk_add_f32 v[158:159], v[158:159], v[180:181] op_sel_hi:[1,0] neg_lo:[0,1] neg_hi:[0,1]
	v_pk_add_f32 v[174:175], v[174:175], v[182:183] op_sel_hi:[1,0] neg_lo:[0,1] neg_hi:[0,1]
	v_pk_mul_f32 v[192:193], v[112:113], v[112:113]
	v_pk_mul_f32 v[194:195], v[128:129], v[128:129]
	v_pk_mul_f32 v[196:197], v[144:145], v[144:145]
	v_pk_mul_f32 v[198:199], v[160:161], v[160:161]
	v_add_f32_e32 v176, v192, v193
	v_add_f32_e32 v178, v194, v195
	v_add_f32_e32 v180, v196, v197
	v_add_f32_e32 v182, v198, v199
	v_pk_mul_f32 v[192:193], v[114:115], v[114:115]
	v_pk_mul_f32 v[194:195], v[130:131], v[130:131]
	v_pk_mul_f32 v[196:197], v[146:147], v[146:147]
	v_pk_mul_f32 v[198:199], v[162:163], v[162:163]
	v_add_f32_e32 v176, v192, v176
	v_add_f32_e32 v178, v194, v178
	v_add_f32_e32 v180, v196, v180
	v_add_f32_e32 v182, v198, v182
	v_add_f32_e32 v176, v193, v176
	v_add_f32_e32 v178, v195, v178
	v_add_f32_e32 v180, v197, v180
	v_add_f32_e32 v182, v199, v182
	v_pk_mul_f32 v[192:193], v[116:117], v[116:117]
	v_pk_mul_f32 v[194:195], v[132:133], v[132:133]
	v_pk_mul_f32 v[196:197], v[148:149], v[148:149]
	v_pk_mul_f32 v[198:199], v[164:165], v[164:165]
	v_add_f32_e32 v176, v192, v176
	v_add_f32_e32 v178, v194, v178
	v_add_f32_e32 v180, v196, v180
	v_add_f32_e32 v182, v198, v182
	v_add_f32_e32 v176, v193, v176
	v_add_f32_e32 v178, v195, v178
	v_add_f32_e32 v180, v197, v180
	v_add_f32_e32 v182, v199, v182
	v_pk_mul_f32 v[192:193], v[118:119], v[118:119]
	v_pk_mul_f32 v[194:195], v[134:135], v[134:135]
	v_pk_mul_f32 v[196:197], v[150:151], v[150:151]
	v_pk_mul_f32 v[198:199], v[166:167], v[166:167]
	v_add_f32_e32 v176, v192, v176
	v_add_f32_e32 v178, v194, v178
	v_add_f32_e32 v180, v196, v180
	v_add_f32_e32 v182, v198, v182
	v_add_f32_e32 v176, v193, v176
	v_add_f32_e32 v178, v195, v178
	v_add_f32_e32 v180, v197, v180
	v_add_f32_e32 v182, v199, v182
	v_pk_mul_f32 v[192:193], v[120:121], v[120:121]
	v_pk_mul_f32 v[194:195], v[136:137], v[136:137]
	v_pk_mul_f32 v[196:197], v[152:153], v[152:153]
	v_pk_mul_f32 v[198:199], v[168:169], v[168:169]
	v_add_f32_e32 v176, v192, v176
	v_add_f32_e32 v178, v194, v178
	v_add_f32_e32 v180, v196, v180
	v_add_f32_e32 v182, v198, v182
	v_add_f32_e32 v176, v193, v176
	v_add_f32_e32 v178, v195, v178
	v_add_f32_e32 v180, v197, v180
	v_add_f32_e32 v182, v199, v182
	v_pk_mul_f32 v[192:193], v[122:123], v[122:123]
	v_pk_mul_f32 v[194:195], v[138:139], v[138:139]
	v_pk_mul_f32 v[196:197], v[154:155], v[154:155]
	v_pk_mul_f32 v[198:199], v[170:171], v[170:171]
	v_add_f32_e32 v176, v192, v176
	v_add_f32_e32 v178, v194, v178
	v_add_f32_e32 v180, v196, v180
	v_add_f32_e32 v182, v198, v182
	v_add_f32_e32 v176, v193, v176
	v_add_f32_e32 v178, v195, v178
	v_add_f32_e32 v180, v197, v180
	v_add_f32_e32 v182, v199, v182
	v_pk_mul_f32 v[192:193], v[124:125], v[124:125]
	v_pk_mul_f32 v[194:195], v[140:141], v[140:141]
	v_pk_mul_f32 v[196:197], v[156:157], v[156:157]
	v_pk_mul_f32 v[198:199], v[172:173], v[172:173]
	v_add_f32_e32 v176, v192, v176
	v_add_f32_e32 v178, v194, v178
	v_add_f32_e32 v180, v196, v180
	v_add_f32_e32 v182, v198, v182
	v_add_f32_e32 v176, v193, v176
	v_add_f32_e32 v178, v195, v178
	v_add_f32_e32 v180, v197, v180
	v_add_f32_e32 v182, v199, v182
	v_pk_mul_f32 v[192:193], v[126:127], v[126:127]
	v_pk_mul_f32 v[194:195], v[142:143], v[142:143]
	v_pk_mul_f32 v[196:197], v[158:159], v[158:159]
	v_pk_mul_f32 v[198:199], v[174:175], v[174:175]
	v_add_f32_e32 v176, v192, v176
	v_add_f32_e32 v178, v194, v178
	v_add_f32_e32 v180, v196, v180
	v_add_f32_e32 v182, v198, v182
	v_add_f32_e32 v176, v193, v176
	v_add_f32_e32 v178, v195, v178
	v_add_f32_e32 v180, v197, v180
	v_add_f32_e32 v182, v199, v182
	ds_bpermute_b32 v188, v2, v176
	ds_bpermute_b32 v189, v2, v178
	ds_bpermute_b32 v190, v2, v180
	ds_bpermute_b32 v191, v2, v182
	s_waitcnt lgkmcnt(0)
	v_add_f32_e32 v176, v176, v188
	v_add_f32_e32 v178, v178, v189
	v_add_f32_e32 v180, v180, v190
	v_add_f32_e32 v182, v182, v191
	ds_bpermute_b32 v188, v3, v176
	ds_bpermute_b32 v189, v3, v178
	ds_bpermute_b32 v190, v3, v180
	ds_bpermute_b32 v191, v3, v182
	s_waitcnt lgkmcnt(0)
	v_add_f32_e32 v176, v176, v188
	v_add_f32_e32 v178, v178, v189
	v_add_f32_e32 v180, v180, v190
	v_add_f32_e32 v182, v182, v191
	ds_bpermute_b32 v188, v4, v176
	ds_bpermute_b32 v189, v4, v178
	ds_bpermute_b32 v190, v4, v180
	ds_bpermute_b32 v191, v4, v182
	s_waitcnt lgkmcnt(0)
	v_add_f32_e32 v176, v176, v188
	v_add_f32_e32 v178, v178, v189
	v_add_f32_e32 v180, v180, v190
	v_add_f32_e32 v182, v182, v191
	ds_bpermute_b32 v188, v5, v176
	ds_bpermute_b32 v189, v5, v178
	ds_bpermute_b32 v190, v5, v180
	ds_bpermute_b32 v191, v5, v182
	s_waitcnt lgkmcnt(0)
	v_add_f32_e32 v176, v176, v188
	v_add_f32_e32 v178, v178, v189
	v_add_f32_e32 v180, v180, v190
	v_add_f32_e32 v182, v182, v191
	ds_bpermute_b32 v188, v6, v176
	ds_bpermute_b32 v189, v6, v178
	ds_bpermute_b32 v190, v6, v180
	ds_bpermute_b32 v191, v6, v182
	s_waitcnt lgkmcnt(0)
	v_add_f32_e32 v176, v176, v188
	v_add_f32_e32 v178, v178, v189
	v_add_f32_e32 v180, v180, v190
	v_add_f32_e32 v182, v182, v191
	ds_bpermute_b32 v188, v7, v176
	ds_bpermute_b32 v189, v7, v178
	ds_bpermute_b32 v190, v7, v180
	ds_bpermute_b32 v191, v7, v182
	s_waitcnt lgkmcnt(0)
	v_add_f32_e32 v176, v176, v188
	v_add_f32_e32 v178, v178, v189
	v_add_f32_e32 v180, v180, v190
	v_add_f32_e32 v182, v182, v191
	v_fmamk_f32 v176, v176, 0x3a800000, v8
	v_fmamk_f32 v178, v178, 0x3a800000, v8
	v_fmamk_f32 v180, v180, 0x3a800000, v8
	v_fmamk_f32 v182, v182, 0x3a800000, v8
	v_rsq_f32_e32 v176, v176
	v_rsq_f32_e32 v178, v178
	v_rsq_f32_e32 v180, v180
	v_rsq_f32_e32 v182, v182
	s_nop 1
	v_pk_mul_f32 v[112:113], v[112:113], v[176:177] op_sel_hi:[1,0]
	v_pk_mul_f32 v[128:129], v[128:129], v[178:179] op_sel_hi:[1,0]
	v_pk_mul_f32 v[144:145], v[144:145], v[180:181] op_sel_hi:[1,0]
	v_pk_mul_f32 v[160:161], v[160:161], v[182:183] op_sel_hi:[1,0]
	v_pk_mul_f32 v[114:115], v[114:115], v[176:177] op_sel_hi:[1,0]
	v_pk_mul_f32 v[130:131], v[130:131], v[178:179] op_sel_hi:[1,0]
	v_pk_mul_f32 v[146:147], v[146:147], v[180:181] op_sel_hi:[1,0]
	v_pk_mul_f32 v[162:163], v[162:163], v[182:183] op_sel_hi:[1,0]
	v_pk_mul_f32 v[116:117], v[116:117], v[176:177] op_sel_hi:[1,0]
	v_pk_mul_f32 v[132:133], v[132:133], v[178:179] op_sel_hi:[1,0]
	v_pk_mul_f32 v[148:149], v[148:149], v[180:181] op_sel_hi:[1,0]
	v_pk_mul_f32 v[164:165], v[164:165], v[182:183] op_sel_hi:[1,0]
	v_pk_mul_f32 v[118:119], v[118:119], v[176:177] op_sel_hi:[1,0]
	v_pk_mul_f32 v[134:135], v[134:135], v[178:179] op_sel_hi:[1,0]
	v_pk_mul_f32 v[150:151], v[150:151], v[180:181] op_sel_hi:[1,0]
	v_pk_mul_f32 v[166:167], v[166:167], v[182:183] op_sel_hi:[1,0]
	v_pk_mul_f32 v[120:121], v[120:121], v[176:177] op_sel_hi:[1,0]
	v_pk_mul_f32 v[136:137], v[136:137], v[178:179] op_sel_hi:[1,0]
	v_pk_mul_f32 v[152:153], v[152:153], v[180:181] op_sel_hi:[1,0]
	v_pk_mul_f32 v[168:169], v[168:169], v[182:183] op_sel_hi:[1,0]
	v_pk_mul_f32 v[122:123], v[122:123], v[176:177] op_sel_hi:[1,0]
	v_pk_mul_f32 v[138:139], v[138:139], v[178:179] op_sel_hi:[1,0]
	v_pk_mul_f32 v[154:155], v[154:155], v[180:181] op_sel_hi:[1,0]
	v_pk_mul_f32 v[170:171], v[170:171], v[182:183] op_sel_hi:[1,0]
	v_pk_mul_f32 v[124:125], v[124:125], v[176:177] op_sel_hi:[1,0]
	v_pk_mul_f32 v[140:141], v[140:141], v[178:179] op_sel_hi:[1,0]
	v_pk_mul_f32 v[156:157], v[156:157], v[180:181] op_sel_hi:[1,0]
	v_pk_mul_f32 v[172:173], v[172:173], v[182:183] op_sel_hi:[1,0]
	v_pk_mul_f32 v[126:127], v[126:127], v[176:177] op_sel_hi:[1,0]
	v_pk_mul_f32 v[142:143], v[142:143], v[178:179] op_sel_hi:[1,0]
	v_pk_mul_f32 v[158:159], v[158:159], v[180:181] op_sel_hi:[1,0]
	v_pk_mul_f32 v[174:175], v[174:175], v[182:183] op_sel_hi:[1,0]
	v_pk_fma_f32 v[112:113], v[112:113], v[16:17], v[32:33]
	v_pk_fma_f32 v[128:129], v[128:129], v[16:17], v[32:33]
	v_pk_fma_f32 v[144:145], v[144:145], v[16:17], v[32:33]
	v_pk_fma_f32 v[160:161], v[160:161], v[16:17], v[32:33]
	v_pk_fma_f32 v[114:115], v[114:115], v[18:19], v[34:35]
	v_pk_fma_f32 v[130:131], v[130:131], v[18:19], v[34:35]
	v_pk_fma_f32 v[146:147], v[146:147], v[18:19], v[34:35]
	v_pk_fma_f32 v[162:163], v[162:163], v[18:19], v[34:35]
	v_pk_fma_f32 v[116:117], v[116:117], v[20:21], v[36:37]
	v_pk_fma_f32 v[132:133], v[132:133], v[20:21], v[36:37]
	v_pk_fma_f32 v[148:149], v[148:149], v[20:21], v[36:37]
	v_pk_fma_f32 v[164:165], v[164:165], v[20:21], v[36:37]
	v_pk_fma_f32 v[118:119], v[118:119], v[22:23], v[38:39]
	v_pk_fma_f32 v[134:135], v[134:135], v[22:23], v[38:39]
	v_pk_fma_f32 v[150:151], v[150:151], v[22:23], v[38:39]
	v_pk_fma_f32 v[166:167], v[166:167], v[22:23], v[38:39]
	v_pk_fma_f32 v[120:121], v[120:121], v[24:25], v[40:41]
	v_pk_fma_f32 v[136:137], v[136:137], v[24:25], v[40:41]
	v_pk_fma_f32 v[152:153], v[152:153], v[24:25], v[40:41]
	v_pk_fma_f32 v[168:169], v[168:169], v[24:25], v[40:41]
	v_pk_fma_f32 v[122:123], v[122:123], v[26:27], v[42:43]
	v_pk_fma_f32 v[138:139], v[138:139], v[26:27], v[42:43]
	v_pk_fma_f32 v[154:155], v[154:155], v[26:27], v[42:43]
	v_pk_fma_f32 v[170:171], v[170:171], v[26:27], v[42:43]
	v_pk_fma_f32 v[124:125], v[124:125], v[28:29], v[44:45]
	v_pk_fma_f32 v[140:141], v[140:141], v[28:29], v[44:45]
	v_pk_fma_f32 v[156:157], v[156:157], v[28:29], v[44:45]
	v_pk_fma_f32 v[172:173], v[172:173], v[28:29], v[44:45]
	v_pk_fma_f32 v[126:127], v[126:127], v[30:31], v[46:47]
	v_pk_fma_f32 v[142:143], v[142:143], v[30:31], v[46:47]
	v_pk_fma_f32 v[158:159], v[158:159], v[30:31], v[46:47]
	v_pk_fma_f32 v[174:175], v[174:175], v[30:31], v[46:47]
	v_cvt_pk_bf16_f32 v200, v112, v113
	v_cvt_pk_bf16_f32 v201, v114, v115
	v_cvt_pk_bf16_f32 v202, v116, v117
	v_cvt_pk_bf16_f32 v203, v118, v119
	v_cvt_pk_bf16_f32 v204, v120, v121
	v_cvt_pk_bf16_f32 v205, v122, v123
	v_cvt_pk_bf16_f32 v206, v124, v125
	v_cvt_pk_bf16_f32 v207, v126, v127
	v_cvt_pk_bf16_f32 v208, v128, v129
	v_cvt_pk_bf16_f32 v209, v130, v131
	v_cvt_pk_bf16_f32 v210, v132, v133
	v_cvt_pk_bf16_f32 v211, v134, v135
	v_cvt_pk_bf16_f32 v212, v136, v137
	v_cvt_pk_bf16_f32 v213, v138, v139
	v_cvt_pk_bf16_f32 v214, v140, v141
	v_cvt_pk_bf16_f32 v215, v142, v143
	v_cvt_pk_bf16_f32 v216, v144, v145
	v_cvt_pk_bf16_f32 v217, v146, v147
	v_cvt_pk_bf16_f32 v218, v148, v149
	v_cvt_pk_bf16_f32 v219, v150, v151
	v_cvt_pk_bf16_f32 v220, v152, v153
	v_cvt_pk_bf16_f32 v221, v154, v155
	v_cvt_pk_bf16_f32 v222, v156, v157
	v_cvt_pk_bf16_f32 v223, v158, v159
	v_cvt_pk_bf16_f32 v224, v160, v161
	v_cvt_pk_bf16_f32 v225, v162, v163
	v_cvt_pk_bf16_f32 v226, v164, v165
	v_cvt_pk_bf16_f32 v227, v166, v167
	v_cvt_pk_bf16_f32 v228, v168, v169
	v_cvt_pk_bf16_f32 v229, v170, v171
	v_cvt_pk_bf16_f32 v230, v172, v173
	v_cvt_pk_bf16_f32 v231, v174, v175
	s_mov_b32 s5, s0
	s_lshl_b32 s4, s5, 11
	s_add_u32 s2, s64, s4
	s_addc_u32 s3, s65, 0
	global_store_dwordx4 v0, v[200:203], s[2:3]
	global_store_dwordx4 v0, v[204:207], s[2:3] offset:1024
	s_mov_b32 s4, s46
	s_add_i32 s5, s0, s4
	s_cmp_lt_i32 s5, 0x8000
	s_cbranch_scc0 .Llnh_ns1_1
	s_lshl_b32 s4, s5, 11
	s_add_u32 s2, s64, s4
	s_addc_u32 s3, s65, 0
	global_store_dwordx4 v0, v[208:211], s[2:3]
	global_store_dwordx4 v0, v[212:215], s[2:3] offset:1024
.Llnh_ns1_1:
	s_mul_i32 s4, s46, 2
	s_add_i32 s5, s0, s4
	s_cmp_lt_i32 s5, 0x8000
	s_cbranch_scc0 .Llnh_ns1_2
	s_lshl_b32 s4, s5, 11
	s_add_u32 s2, s64, s4
	s_addc_u32 s3, s65, 0
	global_store_dwordx4 v0, v[216:219], s[2:3]
	global_store_dwordx4 v0, v[220:223], s[2:3] offset:1024
.Llnh_ns1_2:
	s_mul_i32 s4, s46, 3
	s_add_i32 s5, s0, s4
	s_cmp_lt_i32 s5, 0x8000
	s_cbranch_scc0 .Llnh_ns1_3
	s_lshl_b32 s4, s5, 11
	s_add_u32 s2, s64, s4
	s_addc_u32 s3, s65, 0
	global_store_dwordx4 v0, v[224:227], s[2:3]
	global_store_dwordx4 v0, v[228:231], s[2:3] offset:1024
.Llnh_ns1_3:
	s_nop 1
	s_mov_b32 s0, s1
	s_cmp_lt_i32 s0, 0x8000
	s_cbranch_scc0 .Llnh_done
.Llnh_top1:
	s_waitcnt vmcnt(8)
	v_lshlrev_b32_e32 v112, 16, v80
	v_and_b32_e32 v113, 0xffff0000, v80
	v_lshlrev_b32_e32 v128, 16, v88
	v_and_b32_e32 v129, 0xffff0000, v88
	v_lshlrev_b32_e32 v144, 16, v96
	v_and_b32_e32 v145, 0xffff0000, v96
	v_lshlrev_b32_e32 v160, 16, v104
	v_and_b32_e32 v161, 0xffff0000, v104
	v_lshlrev_b32_e32 v114, 16, v81
	v_and_b32_e32 v115, 0xffff0000, v81
	v_lshlrev_b32_e32 v130, 16, v89
	v_and_b32_e32 v131, 0xffff0000, v89
	v_lshlrev_b32_e32 v146, 16, v97
	v_and_b32_e32 v147, 0xffff0000, v97
	v_lshlrev_b32_e32 v162, 16, v105
	v_and_b32_e32 v163, 0xffff0000, v105
	v_lshlrev_b32_e32 v116, 16, v82
	v_and_b32_e32 v117, 0xffff0000, v82
	v_lshlrev_b32_e32 v132, 16, v90
	v_and_b32_e32 v133, 0xffff0000, v90
	v_lshlrev_b32_e32 v148, 16, v98
	v_and_b32_e32 v149, 0xffff0000, v98
	v_lshlrev_b32_e32 v164, 16, v106
	v_and_b32_e32 v165, 0xffff0000, v106
	v_lshlrev_b32_e32 v118, 16, v83
	v_and_b32_e32 v119, 0xffff0000, v83
	v_lshlrev_b32_e32 v134, 16, v91
	v_and_b32_e32 v135, 0xffff0000, v91
	v_lshlrev_b32_e32 v150, 16, v99
	v_and_b32_e32 v151, 0xffff0000, v99
	v_lshlrev_b32_e32 v166, 16, v107
	v_and_b32_e32 v167, 0xffff0000, v107
	v_lshlrev_b32_e32 v120, 16, v84
	v_and_b32_e32 v121, 0xffff0000, v84
	v_lshlrev_b32_e32 v136, 16, v92
	v_and_b32_e32 v137, 0xffff0000, v92
	v_lshlrev_b32_e32 v152, 16, v100
	v_and_b32_e32 v153, 0xffff0000, v100
	v_lshlrev_b32_e32 v168, 16, v108
	v_and_b32_e32 v169, 0xffff0000, v108
	v_lshlrev_b32_e32 v122, 16, v85
	v_and_b32_e32 v123, 0xffff0000, v85
	v_lshlrev_b32_e32 v138, 16, v93
	v_and_b32_e32 v139, 0xffff0000, v93
	v_lshlrev_b32_e32 v154, 16, v101
	v_and_b32_e32 v155, 0xffff0000, v101
	v_lshlrev_b32_e32 v170, 16, v109
	v_and_b32_e32 v171, 0xffff0000, v109
	v_lshlrev_b32_e32 v124, 16, v86
	v_and_b32_e32 v125, 0xffff0000, v86
	v_lshlrev_b32_e32 v140, 16, v94
	v_and_b32_e32 v141, 0xffff0000, v94
	v_lshlrev_b32_e32 v156, 16, v102
	v_and_b32_e32 v157, 0xffff0000, v102
	v_lshlrev_b32_e32 v172, 16, v110
	v_and_b32_e32 v173, 0xffff0000, v110
	v_lshlrev_b32_e32 v126, 16, v87
	v_and_b32_e32 v127, 0xffff0000, v87
	v_lshlrev_b32_e32 v142, 16, v95
	v_and_b32_e32 v143, 0xffff0000, v95
	v_lshlrev_b32_e32 v158, 16, v103
	v_and_b32_e32 v159, 0xffff0000, v103
	v_lshlrev_b32_e32 v174, 16, v111
	v_and_b32_e32 v175, 0xffff0000, v111
	v_add_f32_e32 v176, v112, v113
	v_add_f32_e32 v178, v128, v129
	v_add_f32_e32 v180, v144, v145
	v_add_f32_e32 v182, v160, v161
	v_add_f32_e32 v176, v176, v114
	v_add_f32_e32 v178, v178, v130
	v_add_f32_e32 v180, v180, v146
	v_add_f32_e32 v182, v182, v162
	v_add_f32_e32 v176, v176, v115
	v_add_f32_e32 v178, v178, v131
	v_add_f32_e32 v180, v180, v147
	v_add_f32_e32 v182, v182, v163
	v_add_f32_e32 v176, v176, v116
	v_add_f32_e32 v178, v178, v132
	v_add_f32_e32 v180, v180, v148
	v_add_f32_e32 v182, v182, v164
	v_add_f32_e32 v176, v176, v117
	v_add_f32_e32 v178, v178, v133
	v_add_f32_e32 v180, v180, v149
	v_add_f32_e32 v182, v182, v165
	v_add_f32_e32 v176, v176, v118
	v_add_f32_e32 v178, v178, v134
	v_add_f32_e32 v180, v180, v150
	v_add_f32_e32 v182, v182, v166
	v_add_f32_e32 v176, v176, v119
	v_add_f32_e32 v178, v178, v135
	v_add_f32_e32 v180, v180, v151
	v_add_f32_e32 v182, v182, v167
	v_add_f32_e32 v176, v176, v120
	v_add_f32_e32 v178, v178, v136
	v_add_f32_e32 v180, v180, v152
	v_add_f32_e32 v182, v182, v168
	v_add_f32_e32 v176, v176, v121
	v_add_f32_e32 v178, v178, v137
	v_add_f32_e32 v180, v180, v153
	v_add_f32_e32 v182, v182, v169
	v_add_f32_e32 v176, v176, v122
	v_add_f32_e32 v178, v178, v138
	v_add_f32_e32 v180, v180, v154
	v_add_f32_e32 v182, v182, v170
	v_add_f32_e32 v176, v176, v123
	v_add_f32_e32 v178, v178, v139
	v_add_f32_e32 v180, v180, v155
	v_add_f32_e32 v182, v182, v171
	v_add_f32_e32 v176, v176, v124
	v_add_f32_e32 v178, v178, v140
	v_add_f32_e32 v180, v180, v156
	v_add_f32_e32 v182, v182, v172
	v_add_f32_e32 v176, v176, v125
	v_add_f32_e32 v178, v178, v141
	v_add_f32_e32 v180, v180, v157
	v_add_f32_e32 v182, v182, v173
	v_add_f32_e32 v176, v176, v126
	v_add_f32_e32 v178, v178, v142
	v_add_f32_e32 v180, v180, v158
	v_add_f32_e32 v182, v182, v174
	v_add_f32_e32 v176, v176, v127
	v_add_f32_e32 v178, v178, v143
	v_add_f32_e32 v180, v180, v159
	v_add_f32_e32 v182, v182, v175
	s_add_i32 s1, s0, s14
	s_cmp_lt_i32 s1, 0x8000
	s_cbranch_scc0 .Llnh_np2
	s_mov_b32 s5, s1
	s_lshl_b32 s4, s5, 11
	s_add_u32 s2, s88, s4
	s_addc_u32 s3, s89, 0
	global_load_dwordx4 v[48:51], v0, s[2:3] nt
	global_load_dwordx4 v[52:55], v0, s[2:3] offset:1024 nt
	s_mov_b32 s4, s46
	s_add_i32 s5, s1, s4
	s_cmp_lt_i32 s5, 0x8000
	s_cselect_b32 s5, s5, s1
	s_lshl_b32 s4, s5, 11
	s_add_u32 s2, s88, s4
	s_addc_u32 s3, s89, 0
	global_load_dwordx4 v[56:59], v0, s[2:3] nt
	global_load_dwordx4 v[60:63], v0, s[2:3] offset:1024 nt
	s_mul_i32 s4, s46, 2
	s_add_i32 s5, s1, s4
	s_cmp_lt_i32 s5, 0x8000
	s_cselect_b32 s5, s5, s1
	s_lshl_b32 s4, s5, 11
	s_add_u32 s2, s88, s4
	s_addc_u32 s3, s89, 0
	global_load_dwordx4 v[64:67], v0, s[2:3] nt
	global_load_dwordx4 v[68:71], v0, s[2:3] offset:1024 nt
	s_mul_i32 s4, s46, 3
	s_add_i32 s5, s1, s4
	s_cmp_lt_i32 s5, 0x8000
	s_cselect_b32 s5, s5, s1
	s_lshl_b32 s4, s5, 11
	s_add_u32 s2, s88, s4
	s_addc_u32 s3, s89, 0
	global_load_dwordx4 v[72:75], v0, s[2:3] nt
	global_load_dwordx4 v[76:79], v0, s[2:3] offset:1024 nt

.Llnh_ns2_3:
	s_nop 1
	s_mov_b32 s0, s1
	s_cmp_lt_i32 s0, 0x8000
	s_cbranch_scc0 .Llnh_done
	s_waitcnt vmcnt(8)
	v_lshlrev_b32_e32 v112, 16, v48
	v_and_b32_e32 v113, 0xffff0000, v48
	v_lshlrev_b32_e32 v128, 16, v56
	v_and_b32_e32 v129, 0xffff0000, v56
	v_lshlrev_b32_e32 v144, 16, v64
	v_and_b32_e32 v145, 0xffff0000, v64
	v_lshlrev_b32_e32 v160, 16, v72
	v_and_b32_e32 v161, 0xffff0000, v72
	v_lshlrev_b32_e32 v114, 16, v49
	v_and_b32_e32 v115, 0xffff0000, v49
	v_lshlrev_b32_e32 v130, 16, v57
	v_and_b32_e32 v131, 0xffff0000, v57
	v_lshlrev_b32_e32 v146, 16, v65
	v_and_b32_e32 v147, 0xffff0000, v65
	v_lshlrev_b32_e32 v162, 16, v73
	v_and_b32_e32 v163, 0xffff0000, v73
	v_lshlrev_b32_e32 v116, 16, v50
	v_and_b32_e32 v117, 0xffff0000, v50
	v_lshlrev_b32_e32 v132, 16, v58
	v_and_b32_e32 v133, 0xffff0000, v58
	v_lshlrev_b32_e32 v148, 16, v66
	v_and_b32_e32 v149, 0xffff0000, v66
	v_lshlrev_b32_e32 v164, 16, v74
	v_and_b32_e32 v165, 0xffff0000, v74
	v_lshlrev_b32_e32 v118, 16, v51
	v_and_b32_e32 v119, 0xffff0000, v51
	v_lshlrev_b32_e32 v134, 16, v59
	v_and_b32_e32 v135, 0xffff0000, v59
	v_lshlrev_b32_e32 v150, 16, v67
	v_and_b32_e32 v151, 0xffff0000, v67
	v_lshlrev_b32_e32 v166, 16, v75
	v_and_b32_e32 v167, 0xffff0000, v75
	v_lshlrev_b32_e32 v120, 16, v52
	v_and_b32_e32 v121, 0xffff0000, v52
	v_lshlrev_b32_e32 v136, 16, v60
	v_and_b32_e32 v137, 0xffff0000, v60
	v_lshlrev_b32_e32 v152, 16, v68
	v_and_b32_e32 v153, 0xffff0000, v68
	v_lshlrev_b32_e32 v168, 16, v76
	v_and_b32_e32 v169, 0xffff0000, v76
	v_lshlrev_b32_e32 v122, 16, v53
	v_and_b32_e32 v123, 0xffff0000, v53
	v_lshlrev_b32_e32 v138, 16, v61
	v_and_b32_e32 v139, 0xffff0000, v61
	v_lshlrev_b32_e32 v154, 16, v69
	v_and_b32_e32 v155, 0xffff0000, v69
	v_lshlrev_b32_e32 v170, 16, v77
	v_and_b32_e32 v171, 0xffff0000, v77
	v_lshlrev_b32_e32 v124, 16, v54
	v_and_b32_e32 v125, 0xffff0000, v54
	v_lshlrev_b32_e32 v140, 16, v62
	v_and_b32_e32 v141, 0xffff0000, v62
	v_lshlrev_b32_e32 v156, 16, v70
	v_and_b32_e32 v157, 0xffff0000, v70
	v_lshlrev_b32_e32 v172, 16, v78
	v_and_b32_e32 v173, 0xffff0000, v78
	v_lshlrev_b32_e32 v126, 16, v55
	v_and_b32_e32 v127, 0xffff0000, v55
	v_lshlrev_b32_e32 v142, 16, v63
	v_and_b32_e32 v143, 0xffff0000, v63
	v_lshlrev_b32_e32 v158, 16, v71
	v_and_b32_e32 v159, 0xffff0000, v71
	v_lshlrev_b32_e32 v174, 16, v79
	v_and_b32_e32 v175, 0xffff0000, v79
	v_add_f32_e32 v176, v112, v113
	v_add_f32_e32 v178, v128, v129
	v_add_f32_e32 v180, v144, v145
	v_add_f32_e32 v182, v160, v161
	v_add_f32_e32 v176, v176, v114
	v_add_f32_e32 v178, v178, v130
	v_add_f32_e32 v180, v180, v146
	v_add_f32_e32 v182, v182, v162
	v_add_f32_e32 v176, v176, v115
	v_add_f32_e32 v178, v178, v131
	v_add_f32_e32 v180, v180, v147
	v_add_f32_e32 v182, v182, v163
	v_add_f32_e32 v176, v176, v116
	v_add_f32_e32 v178, v178, v132
	v_add_f32_e32 v180, v180, v148
	v_add_f32_e32 v182, v182, v164
	v_add_f32_e32 v176, v176, v117
	v_add_f32_e32 v178, v178, v133
	v_add_f32_e32 v180, v180, v149
	v_add_f32_e32 v182, v182, v165
	v_add_f32_e32 v176, v176, v118
	v_add_f32_e32 v178, v178, v134
	v_add_f32_e32 v180, v180, v150
	v_add_f32_e32 v182, v182, v166
	v_add_f32_e32 v176, v176, v119
	v_add_f32_e32 v178, v178, v135
	v_add_f32_e32 v180, v180, v151
	v_add_f32_e32 v182, v182, v167
	v_add_f32_e32 v176, v176, v120
	v_add_f32_e32 v178, v178, v136
	v_add_f32_e32 v180, v180, v152
	v_add_f32_e32 v182, v182, v168
	v_add_f32_e32 v176, v176, v121
	v_add_f32_e32 v178, v178, v137
	v_add_f32_e32 v180, v180, v153
	v_add_f32_e32 v182, v182, v169
	v_add_f32_e32 v176, v176, v122
	v_add_f32_e32 v178, v178, v138
	v_add_f32_e32 v180, v180, v154
	v_add_f32_e32 v182, v182, v170
	v_add_f32_e32 v176, v176, v123
	v_add_f32_e32 v178, v178, v139
	v_add_f32_e32 v180, v180, v155
	v_add_f32_e32 v182, v182, v171
	v_add_f32_e32 v176, v176, v124
	v_add_f32_e32 v178, v178, v140
	v_add_f32_e32 v180, v180, v156
	v_add_f32_e32 v182, v182, v172
	v_add_f32_e32 v176, v176, v125
	v_add_f32_e32 v178, v178, v141
	v_add_f32_e32 v180, v180, v157
	v_add_f32_e32 v182, v182, v173
	v_add_f32_e32 v176, v176, v126
	v_add_f32_e32 v178, v178, v142
	v_add_f32_e32 v180, v180, v158
	v_add_f32_e32 v182, v182, v174
	v_add_f32_e32 v176, v176, v127
	v_add_f32_e32 v178, v178, v143
	v_add_f32_e32 v180, v180, v159
	v_add_f32_e32 v182, v182, v175
	s_add_i32 s1, s0, s14
	s_cmp_lt_i32 s1, 0x8000
	s_cbranch_scc0 .Llnh_np3
	s_mov_b32 s5, s1
	s_lshl_b32 s4, s5, 11
	s_add_u32 s2, s88, s4
	s_addc_u32 s3, s89, 0
	global_load_dwordx4 v[80:83], v0, s[2:3] nt
	global_load_dwordx4 v[84:87], v0, s[2:3] offset:1024 nt
	s_mov_b32 s4, s46
	s_add_i32 s5, s1, s4
	s_cmp_lt_i32 s5, 0x8000
	s_cselect_b32 s5, s5, s1
	s_lshl_b32 s4, s5, 11
	s_add_u32 s2, s88, s4
	s_addc_u32 s3, s89, 0
	global_load_dwordx4 v[88:91], v0, s[2:3] nt
	global_load_dwordx4 v[92:95], v0, s[2:3] offset:1024 nt
	s_mul_i32 s4, s46, 2
	s_add_i32 s5, s1, s4
	s_cmp_lt_i32 s5, 0x8000
	s_cselect_b32 s5, s5, s1
	s_lshl_b32 s4, s5, 11
	s_add_u32 s2, s88, s4
	s_addc_u32 s3, s89, 0
	global_load_dwordx4 v[96:99], v0, s[2:3] nt
	global_load_dwordx4 v[100:103], v0, s[2:3] offset:1024 nt
	s_mul_i32 s4, s46, 3
	s_add_i32 s5, s1, s4
	s_cmp_lt_i32 s5, 0x8000
	s_cselect_b32 s5, s5, s1
	s_lshl_b32 s4, s5, 11
	s_add_u32 s2, s88, s4
	s_addc_u32 s3, s89, 0
	global_load_dwordx4 v[104:107], v0, s[2:3] nt
	global_load_dwordx4 v[108:111], v0, s[2:3] offset:1024 nt

.Llnh_ns3_3:
	s_nop 1
	s_mov_b32 s0, s1
	s_cmp_lt_i32 s0, 0x8000
	s_cbranch_scc1 .Llnh_top1
.Llnh_done:
.LBB0_559:
	s_cmp_lt_i32 s71, 11
	s_cbranch_scc1 .LBB0_570
	s_waitcnt vmcnt(0)
	s_add_i32 s66, s66, 1
	s_waitcnt lgkmcnt(0)
	s_barrier
	s_mov_b64 s[0:1], exec
	v_readlane_b32 s2, v254, 0
	v_readlane_b32 s3, v254, 1
	s_and_b64 s[2:3], s[0:1], s[2:3]
	s_mov_b64 exec, s[2:3]
	s_cbranch_execz .LBB0_569
	s_mov_b64 s[4:5], exec
	v_mbcnt_lo_u32_b32 v0, s4, 0
	v_mbcnt_hi_u32_b32 v0, s5, v0
	v_cmp_eq_u32_e32 vcc, 0, v0
	s_and_saveexec_b64 s[2:3], vcc
	s_cbranch_execz .LBB0_563
	s_bcnt1_i32_b64 s4, s[4:5]
	v_mov_b32_e32 v2, s4
	v_readlane_b32 s4, v254, 34
	v_mov_b32_e32 v1, 0
	v_readlane_b32 s5, v254, 35
	s_nop 4
	global_atomic_add v1, v1, v2, s[4:5] offset:256 sc0

.LBB0_674:
	s_cmp_lt_i32 s70, 16
	s_cselect_b64 s[0:1], -1, 0
	s_cmp_gt_i32 s71, 15
	s_cselect_b64 s[2:3], -1, 0
	s_cmp_lt_i32 s94, 0x8000
	s_cselect_b64 s[4:5], -1, 0
	s_and_b64 s[0:1], s[0:1], s[4:5]
	s_and_b64 s[0:1], s[0:1], s[2:3]
	s_andn2_b64 vcc, exec, s[0:1]
	s_cbranch_vccnz .LBB0_681
	v_readlane_b32 s6, v254, 28
	v_readlane_b32 s7, v254, 29
	v_readlane_b32 s8, v254, 30
	v_readlane_b32 s9, v254, 31
	v_readlane_b32 s10, v254, 32
	v_readlane_b32 s11, v254, 33
	s_nop 4
	s_cmp_lt_i32 s94, 0x8000
	s_cbranch_scc0 .Llnf_done
	v_lshlrev_b32_e32 v0, 4, v184
	v_lshlrev_b32_e32 v1, 5, v184
	v_xor_b32_e32 v2, 1, v184
	v_lshlrev_b32_e32 v2, 2, v2
	v_xor_b32_e32 v3, 2, v184
	v_lshlrev_b32_e32 v3, 2, v3
	v_xor_b32_e32 v4, 4, v184
	v_lshlrev_b32_e32 v4, 2, v4
	v_xor_b32_e32 v5, 8, v184
	v_lshlrev_b32_e32 v5, 2, v5
	v_xor_b32_e32 v6, 16, v184
	v_lshlrev_b32_e32 v6, 2, v6
	v_xor_b32_e32 v7, 32, v184
	v_lshlrev_b32_e32 v7, 2, v7
	v_mov_b32_e32 v8, 0x3727c5ac
	global_load_dwordx4 v[16:19], v1, s[6:7]
	global_load_dwordx4 v[20:23], v1, s[6:7] offset:16
	global_load_dwordx4 v[24:27], v1, s[6:7] offset:2048
	global_load_dwordx4 v[28:31], v1, s[6:7] offset:2064
	global_load_dwordx4 v[32:35], v1, s[8:9]
	global_load_dwordx4 v[36:39], v1, s[8:9] offset:16
	global_load_dwordx4 v[40:43], v1, s[8:9] offset:2048
	global_load_dwordx4 v[44:47], v1, s[8:9] offset:2064
	s_mov_b32 s0, s94
	s_lshl_b32 s14, s46, 2
	s_mov_b32 s5, s0
	s_lshl_b32 s4, s5, 11
	s_add_u32 s2, s62, s4
	s_addc_u32 s3, s63, 0
	global_load_dwordx4 v[48:51], v0, s[2:3] nt
	global_load_dwordx4 v[52:55], v0, s[2:3] offset:1024 nt
	s_mov_b32 s4, s46
	s_add_i32 s5, s0, s4
	s_cmp_lt_i32 s5, 0x8000
	s_cselect_b32 s5, s5, s0
	s_lshl_b32 s4, s5, 11
	s_add_u32 s2, s62, s4
	s_addc_u32 s3, s63, 0
	global_load_dwordx4 v[56:59], v0, s[2:3] nt
	global_load_dwordx4 v[60:63], v0, s[2:3] offset:1024 nt
	s_mul_i32 s4, s46, 2
	s_add_i32 s5, s0, s4
	s_cmp_lt_i32 s5, 0x8000
	s_cselect_b32 s5, s5, s0
	s_lshl_b32 s4, s5, 11
	s_add_u32 s2, s62, s4
	s_addc_u32 s3, s63, 0
	global_load_dwordx4 v[64:67], v0, s[2:3] nt
	global_load_dwordx4 v[68:71], v0, s[2:3] offset:1024 nt
	s_mul_i32 s4, s46, 3
	s_add_i32 s5, s0, s4
	s_cmp_lt_i32 s5, 0x8000
	s_cselect_b32 s5, s5, s0
	s_lshl_b32 s4, s5, 11
	s_add_u32 s2, s62, s4
	s_addc_u32 s3, s63, 0
	global_load_dwordx4 v[72:75], v0, s[2:3] nt
	global_load_dwordx4 v[76:79], v0, s[2:3] offset:1024 nt
.Llnf_top:
	s_waitcnt vmcnt(0)
	v_lshlrev_b32_e32 v112, 16, v48
	v_and_b32_e32 v113, 0xffff0000, v48
	v_lshlrev_b32_e32 v128, 16, v56
	v_and_b32_e32 v129, 0xffff0000, v56
	v_lshlrev_b32_e32 v144, 16, v64
	v_and_b32_e32 v145, 0xffff0000, v64
	v_lshlrev_b32_e32 v160, 16, v72
	v_and_b32_e32 v161, 0xffff0000, v72
	v_lshlrev_b32_e32 v114, 16, v49
	v_and_b32_e32 v115, 0xffff0000, v49
	v_lshlrev_b32_e32 v130, 16, v57
	v_and_b32_e32 v131, 0xffff0000, v57
	v_lshlrev_b32_e32 v146, 16, v65
	v_and_b32_e32 v147, 0xffff0000, v65
	v_lshlrev_b32_e32 v162, 16, v73
	v_and_b32_e32 v163, 0xffff0000, v73
	v_lshlrev_b32_e32 v116, 16, v50
	v_and_b32_e32 v117, 0xffff0000, v50
	v_lshlrev_b32_e32 v132, 16, v58
	v_and_b32_e32 v133, 0xffff0000, v58
	v_lshlrev_b32_e32 v148, 16, v66
	v_and_b32_e32 v149, 0xffff0000, v66
	v_lshlrev_b32_e32 v164, 16, v74
	v_and_b32_e32 v165, 0xffff0000, v74
	v_lshlrev_b32_e32 v118, 16, v51
	v_and_b32_e32 v119, 0xffff0000, v51
	v_lshlrev_b32_e32 v134, 16, v59
	v_and_b32_e32 v135, 0xffff0000, v59
	v_lshlrev_b32_e32 v150, 16, v67
	v_and_b32_e32 v151, 0xffff0000, v67
	v_lshlrev_b32_e32 v166, 16, v75
	v_and_b32_e32 v167, 0xffff0000, v75
	v_lshlrev_b32_e32 v120, 16, v52
	v_and_b32_e32 v121, 0xffff0000, v52
	v_lshlrev_b32_e32 v136, 16, v60
	v_and_b32_e32 v137, 0xffff0000, v60
	v_lshlrev_b32_e32 v152, 16, v68
	v_and_b32_e32 v153, 0xffff0000, v68
	v_lshlrev_b32_e32 v168, 16, v76
	v_and_b32_e32 v169, 0xffff0000, v76
	v_lshlrev_b32_e32 v122, 16, v53
	v_and_b32_e32 v123, 0xffff0000, v53
	v_lshlrev_b32_e32 v138, 16, v61
	v_and_b32_e32 v139, 0xffff0000, v61
	v_lshlrev_b32_e32 v154, 16, v69
	v_and_b32_e32 v155, 0xffff0000, v69
	v_lshlrev_b32_e32 v170, 16, v77
	v_and_b32_e32 v171, 0xffff0000, v77
	v_lshlrev_b32_e32 v124, 16, v54
	v_and_b32_e32 v125, 0xffff0000, v54
	v_lshlrev_b32_e32 v140, 16, v62
	v_and_b32_e32 v141, 0xffff0000, v62
	v_lshlrev_b32_e32 v156, 16, v70
	v_and_b32_e32 v157, 0xffff0000, v70
	v_lshlrev_b32_e32 v172, 16, v78
	v_and_b32_e32 v173, 0xffff0000, v78
	v_lshlrev_b32_e32 v126, 16, v55
	v_and_b32_e32 v127, 0xffff0000, v55
	v_lshlrev_b32_e32 v142, 16, v63
	v_and_b32_e32 v143, 0xffff0000, v63
	v_lshlrev_b32_e32 v158, 16, v71
	v_and_b32_e32 v159, 0xffff0000, v71
	v_lshlrev_b32_e32 v174, 16, v79
	v_and_b32_e32 v175, 0xffff0000, v79
	v_add_f32_e32 v176, v112, v113
	v_add_f32_e32 v178, v128, v129
	v_add_f32_e32 v180, v144, v145
	v_add_f32_e32 v182, v160, v161
	v_add_f32_e32 v176, v176, v114
	v_add_f32_e32 v178, v178, v130
	v_add_f32_e32 v180, v180, v146
	v_add_f32_e32 v182, v182, v162
	v_add_f32_e32 v176, v176, v115
	v_add_f32_e32 v178, v178, v131
	v_add_f32_e32 v180, v180, v147
	v_add_f32_e32 v182, v182, v163
	v_add_f32_e32 v176, v176, v116
	v_add_f32_e32 v178, v178, v132
	v_add_f32_e32 v180, v180, v148
	v_add_f32_e32 v182, v182, v164
	v_add_f32_e32 v176, v176, v117
	v_add_f32_e32 v178, v178, v133
	v_add_f32_e32 v180, v180, v149
	v_add_f32_e32 v182, v182, v165
	v_add_f32_e32 v176, v176, v118
	v_add_f32_e32 v178, v178, v134
	v_add_f32_e32 v180, v180, v150
	v_add_f32_e32 v182, v182, v166
	v_add_f32_e32 v176, v176, v119
	v_add_f32_e32 v178, v178, v135
	v_add_f32_e32 v180, v180, v151
	v_add_f32_e32 v182, v182, v167
	v_add_f32_e32 v176, v176, v120
	v_add_f32_e32 v178, v178, v136
	v_add_f32_e32 v180, v180, v152
	v_add_f32_e32 v182, v182, v168
	v_add_f32_e32 v176, v176, v121
	v_add_f32_e32 v178, v178, v137
	v_add_f32_e32 v180, v180, v153
	v_add_f32_e32 v182, v182, v169
	v_add_f32_e32 v176, v176, v122
	v_add_f32_e32 v178, v178, v138
	v_add_f32_e32 v180, v180, v154
	v_add_f32_e32 v182, v182, v170
	v_add_f32_e32 v176, v176, v123
	v_add_f32_e32 v178, v178, v139
	v_add_f32_e32 v180, v180, v155
	v_add_f32_e32 v182, v182, v171
	v_add_f32_e32 v176, v176, v124
	v_add_f32_e32 v178, v178, v140
	v_add_f32_e32 v180, v180, v156
	v_add_f32_e32 v182, v182, v172
	v_add_f32_e32 v176, v176, v125
	v_add_f32_e32 v178, v178, v141
	v_add_f32_e32 v180, v180, v157
	v_add_f32_e32 v182, v182, v173
	v_add_f32_e32 v176, v176, v126
	v_add_f32_e32 v178, v178, v142
	v_add_f32_e32 v180, v180, v158
	v_add_f32_e32 v182, v182, v174
	v_add_f32_e32 v176, v176, v127
	v_add_f32_e32 v178, v178, v143
	v_add_f32_e32 v180, v180, v159
	v_add_f32_e32 v182, v182, v175
	s_add_i32 s1, s0, s14
	s_cmp_lt_i32 s1, 0x8000
	s_cbranch_scc0 .Llnf_np1
	s_mov_b32 s5, s1
	s_lshl_b32 s4, s5, 11
	s_add_u32 s2, s62, s4
	s_addc_u32 s3, s63, 0
	global_load_dwordx4 v[80:83], v0, s[2:3] nt
	global_load_dwordx4 v[84:87], v0, s[2:3] offset:1024 nt
	s_mov_b32 s4, s46
	s_add_i32 s5, s1, s4
	s_cmp_lt_i32 s5, 0x8000
	s_cselect_b32 s5, s5, s1
	s_lshl_b32 s4, s5, 11
	s_add_u32 s2, s62, s4
	s_addc_u32 s3, s63, 0
	global_load_dwordx4 v[88:91], v0, s[2:3] nt
	global_load_dwordx4 v[92:95], v0, s[2:3] offset:1024 nt
	s_mul_i32 s4, s46, 2
	s_add_i32 s5, s1, s4
	s_cmp_lt_i32 s5, 0x8000
	s_cselect_b32 s5, s5, s1
	s_lshl_b32 s4, s5, 11
	s_add_u32 s2, s62, s4
	s_addc_u32 s3, s63, 0
	global_load_dwordx4 v[96:99], v0, s[2:3] nt
	global_load_dwordx4 v[100:103], v0, s[2:3] offset:1024 nt
	s_mul_i32 s4, s46, 3
	s_add_i32 s5, s1, s4
	s_cmp_lt_i32 s5, 0x8000
	s_cselect_b32 s5, s5, s1
	s_lshl_b32 s4, s5, 11
	s_add_u32 s2, s62, s4
	s_addc_u32 s3, s63, 0
	global_load_dwordx4 v[104:107], v0, s[2:3] nt
	global_load_dwordx4 v[108:111], v0, s[2:3] offset:1024 nt
.Llnf_np1:
	ds_bpermute_b32 v188, v2, v176
	ds_bpermute_b32 v189, v2, v178
	ds_bpermute_b32 v190, v2, v180
	ds_bpermute_b32 v191, v2, v182
	s_waitcnt lgkmcnt(0)
	v_add_f32_e32 v176, v176, v188
	v_add_f32_e32 v178, v178, v189
	v_add_f32_e32 v180, v180, v190
	v_add_f32_e32 v182, v182, v191
	ds_bpermute_b32 v188, v3, v176
	ds_bpermute_b32 v189, v3, v178
	ds_bpermute_b32 v190, v3, v180
	ds_bpermute_b32 v191, v3, v182
	s_waitcnt lgkmcnt(0)
	v_add_f32_e32 v176, v176, v188
	v_add_f32_e32 v178, v178, v189
	v_add_f32_e32 v180, v180, v190
	v_add_f32_e32 v182, v182, v191
	ds_bpermute_b32 v188, v4, v176
	ds_bpermute_b32 v189, v4, v178
	ds_bpermute_b32 v190, v4, v180
	ds_bpermute_b32 v191, v4, v182
	s_waitcnt lgkmcnt(0)
	v_add_f32_e32 v176, v176, v188
	v_add_f32_e32 v178, v178, v189
	v_add_f32_e32 v180, v180, v190
	v_add_f32_e32 v182, v182, v191
	ds_bpermute_b32 v188, v5, v176
	ds_bpermute_b32 v189, v5, v178
	ds_bpermute_b32 v190, v5, v180
	ds_bpermute_b32 v191, v5, v182
	s_waitcnt lgkmcnt(0)
	v_add_f32_e32 v176, v176, v188
	v_add_f32_e32 v178, v178, v189
	v_add_f32_e32 v180, v180, v190
	v_add_f32_e32 v182, v182, v191
	ds_bpermute_b32 v188, v6, v176
	ds_bpermute_b32 v189, v6, v178
	ds_bpermute_b32 v190, v6, v180
	ds_bpermute_b32 v191, v6, v182
	s_waitcnt lgkmcnt(0)
	v_add_f32_e32 v176, v176, v188
	v_add_f32_e32 v178, v178, v189
	v_add_f32_e32 v180, v180, v190
	v_add_f32_e32 v182, v182, v191
	ds_bpermute_b32 v188, v7, v176
	ds_bpermute_b32 v189, v7, v178
	ds_bpermute_b32 v190, v7, v180
	ds_bpermute_b32 v191, v7, v182
	s_waitcnt lgkmcnt(0)
	v_add_f32_e32 v176, v176, v188
	v_add_f32_e32 v178, v178, v189
	v_add_f32_e32 v180, v180, v190
	v_add_f32_e32 v182, v182, v191
	v_mul_f32_e32 v176, 0x3a800000, v176
	v_mul_f32_e32 v178, 0x3a800000, v178
	v_mul_f32_e32 v180, 0x3a800000, v180
	v_mul_f32_e32 v182, 0x3a800000, v182
	v_pk_add_f32 v[112:113], v[112:113], v[176:177] op_sel_hi:[1,0] neg_lo:[0,1] neg_hi:[0,1]
	v_pk_add_f32 v[128:129], v[128:129], v[178:179] op_sel_hi:[1,0] neg_lo:[0,1] neg_hi:[0,1]
	v_pk_add_f32 v[144:145], v[144:145], v[180:181] op_sel_hi:[1,0] neg_lo:[0,1] neg_hi:[0,1]
	v_pk_add_f32 v[160:161], v[160:161], v[182:183] op_sel_hi:[1,0] neg_lo:[0,1] neg_hi:[0,1]
	v_pk_add_f32 v[114:115], v[114:115], v[176:177] op_sel_hi:[1,0] neg_lo:[0,1] neg_hi:[0,1]
	v_pk_add_f32 v[130:131], v[130:131], v[178:179] op_sel_hi:[1,0] neg_lo:[0,1] neg_hi:[0,1]
	v_pk_add_f32 v[146:147], v[146:147], v[180:181] op_sel_hi:[1,0] neg_lo:[0,1] neg_hi:[0,1]
	v_pk_add_f32 v[162:163], v[162:163], v[182:183] op_sel_hi:[1,0] neg_lo:[0,1] neg_hi:[0,1]
	v_pk_add_f32 v[116:117], v[116:117], v[176:177] op_sel_hi:[1,0] neg_lo:[0,1] neg_hi:[0,1]
	v_pk_add_f32 v[132:133], v[132:133], v[178:179] op_sel_hi:[1,0] neg_lo:[0,1] neg_hi:[0,1]
	v_pk_add_f32 v[148:149], v[148:149], v[180:181] op_sel_hi:[1,0] neg_lo:[0,1] neg_hi:[0,1]
	v_pk_add_f32 v[164:165], v[164:165], v[182:183] op_sel_hi:[1,0] neg_lo:[0,1] neg_hi:[0,1]
	v_pk_add_f32 v[118:119], v[118:119], v[176:177] op_sel_hi:[1,0] neg_lo:[0,1] neg_hi:[0,1]
	v_pk_add_f32 v[134:135], v[134:135], v[178:179] op_sel_hi:[1,0] neg_lo:[0,1] neg_hi:[0,1]
	v_pk_add_f32 v[150:151], v[150:151], v[180:181] op_sel_hi:[1,0] neg_lo:[0,1] neg_hi:[0,1]
	v_pk_add_f32 v[166:167], v[166:167], v[182:183] op_sel_hi:[1,0] neg_lo:[0,1] neg_hi:[0,1]
	v_pk_add_f32 v[120:121], v[120:121], v[176:177] op_sel_hi:[1,0] neg_lo:[0,1] neg_hi:[0,1]
	v_pk_add_f32 v[136:137], v[136:137], v[178:179] op_sel_hi:[1,0] neg_lo:[0,1] neg_hi:[0,1]
	v_pk_add_f32 v[152:153], v[152:153], v[180:181] op_sel_hi:[1,0] neg_lo:[0,1] neg_hi:[0,1]
	v_pk_add_f32 v[168:169], v[168:169], v[182:183] op_sel_hi:[1,0] neg_lo:[0,1] neg_hi:[0,1]
	v_pk_add_f32 v[122:123], v[122:123], v[176:177] op_sel_hi:[1,0] neg_lo:[0,1] neg_hi:[0,1]
	v_pk_add_f32 v[138:139], v[138:139], v[178:179] op_sel_hi:[1,0] neg_lo:[0,1] neg_hi:[0,1]
	v_pk_add_f32 v[154:155], v[154:155], v[180:181] op_sel_hi:[1,0] neg_lo:[0,1] neg_hi:[0,1]
	v_pk_add_f32 v[170:171], v[170:171], v[182:183] op_sel_hi:[1,0] neg_lo:[0,1] neg_hi:[0,1]
	v_pk_add_f32 v[124:125], v[124:125], v[176:177] op_sel_hi:[1,0] neg_lo:[0,1] neg_hi:[0,1]
	v_pk_add_f32 v[140:141], v[140:141], v[178:179] op_sel_hi:[1,0] neg_lo:[0,1] neg_hi:[0,1]
	v_pk_add_f32 v[156:157], v[156:157], v[180:181] op_sel_hi:[1,0] neg_lo:[0,1] neg_hi:[0,1]
	v_pk_add_f32 v[172:173], v[172:173], v[182:183] op_sel_hi:[1,0] neg_lo:[0,1] neg_hi:[0,1]
	v_pk_add_f32 v[126:127], v[126:127], v[176:177] op_sel_hi:[1,0] neg_lo:[0,1] neg_hi:[0,1]
	v_pk_add_f32 v[142:143], v[142:143], v[178:179] op_sel_hi:[1,0] neg_lo:[0,1] neg_hi:[0,1]
	v_pk_add_f32 v[158:159], v[158:159], v[180:181] op_sel_hi:[1,0] neg_lo:[0,1] neg_hi:[0,1]
	v_pk_add_f32 v[174:175], v[174:175], v[182:183] op_sel_hi:[1,0] neg_lo:[0,1] neg_hi:[0,1]
	v_pk_mul_f32 v[192:193], v[112:113], v[112:113]
	v_pk_mul_f32 v[194:195], v[128:129], v[128:129]
	v_pk_mul_f32 v[196:197], v[144:145], v[144:145]
	v_pk_mul_f32 v[198:199], v[160:161], v[160:161]
	v_add_f32_e32 v176, v192, v193
	v_add_f32_e32 v178, v194, v195
	v_add_f32_e32 v180, v196, v197
	v_add_f32_e32 v182, v198, v199
	v_pk_mul_f32 v[192:193], v[114:115], v[114:115]
	v_pk_mul_f32 v[194:195], v[130:131], v[130:131]
	v_pk_mul_f32 v[196:197], v[146:147], v[146:147]
	v_pk_mul_f32 v[198:199], v[162:163], v[162:163]
	v_add_f32_e32 v176, v192, v176
	v_add_f32_e32 v178, v194, v178
	v_add_f32_e32 v180, v196, v180
	v_add_f32_e32 v182, v198, v182
	v_add_f32_e32 v176, v193, v176
	v_add_f32_e32 v178, v195, v178
	v_add_f32_e32 v180, v197, v180
	v_add_f32_e32 v182, v199, v182
	v_pk_mul_f32 v[192:193], v[116:117], v[116:117]
	v_pk_mul_f32 v[194:195], v[132:133], v[132:133]
	v_pk_mul_f32 v[196:197], v[148:149], v[148:149]
	v_pk_mul_f32 v[198:199], v[164:165], v[164:165]
	v_add_f32_e32 v176, v192, v176
	v_add_f32_e32 v178, v194, v178
	v_add_f32_e32 v180, v196, v180
	v_add_f32_e32 v182, v198, v182
	v_add_f32_e32 v176, v193, v176
	v_add_f32_e32 v178, v195, v178
	v_add_f32_e32 v180, v197, v180
	v_add_f32_e32 v182, v199, v182
	v_pk_mul_f32 v[192:193], v[118:119], v[118:119]
	v_pk_mul_f32 v[194:195], v[134:135], v[134:135]
	v_pk_mul_f32 v[196:197], v[150:151], v[150:151]
	v_pk_mul_f32 v[198:199], v[166:167], v[166:167]
	v_add_f32_e32 v176, v192, v176
	v_add_f32_e32 v178, v194, v178
	v_add_f32_e32 v180, v196, v180
	v_add_f32_e32 v182, v198, v182
	v_add_f32_e32 v176, v193, v176
	v_add_f32_e32 v178, v195, v178
	v_add_f32_e32 v180, v197, v180
	v_add_f32_e32 v182, v199, v182
	v_pk_mul_f32 v[192:193], v[120:121], v[120:121]
	v_pk_mul_f32 v[194:195], v[136:137], v[136:137]
	v_pk_mul_f32 v[196:197], v[152:153], v[152:153]
	v_pk_mul_f32 v[198:199], v[168:169], v[168:169]
	v_add_f32_e32 v176, v192, v176
	v_add_f32_e32 v178, v194, v178
	v_add_f32_e32 v180, v196, v180
	v_add_f32_e32 v182, v198, v182
	v_add_f32_e32 v176, v193, v176
	v_add_f32_e32 v178, v195, v178
	v_add_f32_e32 v180, v197, v180
	v_add_f32_e32 v182, v199, v182
	v_pk_mul_f32 v[192:193], v[122:123], v[122:123]
	v_pk_mul_f32 v[194:195], v[138:139], v[138:139]
	v_pk_mul_f32 v[196:197], v[154:155], v[154:155]
	v_pk_mul_f32 v[198:199], v[170:171], v[170:171]
	v_add_f32_e32 v176, v192, v176
	v_add_f32_e32 v178, v194, v178
	v_add_f32_e32 v180, v196, v180
	v_add_f32_e32 v182, v198, v182
	v_add_f32_e32 v176, v193, v176
	v_add_f32_e32 v178, v195, v178
	v_add_f32_e32 v180, v197, v180
	v_add_f32_e32 v182, v199, v182
	v_pk_mul_f32 v[192:193], v[124:125], v[124:125]
	v_pk_mul_f32 v[194:195], v[140:141], v[140:141]
	v_pk_mul_f32 v[196:197], v[156:157], v[156:157]
	v_pk_mul_f32 v[198:199], v[172:173], v[172:173]
	v_add_f32_e32 v176, v192, v176
	v_add_f32_e32 v178, v194, v178
	v_add_f32_e32 v180, v196, v180
	v_add_f32_e32 v182, v198, v182
	v_add_f32_e32 v176, v193, v176
	v_add_f32_e32 v178, v195, v178
	v_add_f32_e32 v180, v197, v180
	v_add_f32_e32 v182, v199, v182
	v_pk_mul_f32 v[192:193], v[126:127], v[126:127]
	v_pk_mul_f32 v[194:195], v[142:143], v[142:143]
	v_pk_mul_f32 v[196:197], v[158:159], v[158:159]
	v_pk_mul_f32 v[198:199], v[174:175], v[174:175]
	v_add_f32_e32 v176, v192, v176
	v_add_f32_e32 v178, v194, v178
	v_add_f32_e32 v180, v196, v180
	v_add_f32_e32 v182, v198, v182
	v_add_f32_e32 v176, v193, v176
	v_add_f32_e32 v178, v195, v178
	v_add_f32_e32 v180, v197, v180
	v_add_f32_e32 v182, v199, v182
	ds_bpermute_b32 v188, v2, v176
	ds_bpermute_b32 v189, v2, v178
	ds_bpermute_b32 v190, v2, v180
	ds_bpermute_b32 v191, v2, v182
	s_waitcnt lgkmcnt(0)
	v_add_f32_e32 v176, v176, v188
	v_add_f32_e32 v178, v178, v189
	v_add_f32_e32 v180, v180, v190
	v_add_f32_e32 v182, v182, v191
	ds_bpermute_b32 v188, v3, v176
	ds_bpermute_b32 v189, v3, v178
	ds_bpermute_b32 v190, v3, v180
	ds_bpermute_b32 v191, v3, v182
	s_waitcnt lgkmcnt(0)
	v_add_f32_e32 v176, v176, v188
	v_add_f32_e32 v178, v178, v189
	v_add_f32_e32 v180, v180, v190
	v_add_f32_e32 v182, v182, v191
	ds_bpermute_b32 v188, v4, v176
	ds_bpermute_b32 v189, v4, v178
	ds_bpermute_b32 v190, v4, v180
	ds_bpermute_b32 v191, v4, v182
	s_waitcnt lgkmcnt(0)
	v_add_f32_e32 v176, v176, v188
	v_add_f32_e32 v178, v178, v189
	v_add_f32_e32 v180, v180, v190
	v_add_f32_e32 v182, v182, v191
	ds_bpermute_b32 v188, v5, v176
	ds_bpermute_b32 v189, v5, v178
	ds_bpermute_b32 v190, v5, v180
	ds_bpermute_b32 v191, v5, v182
	s_waitcnt lgkmcnt(0)
	v_add_f32_e32 v176, v176, v188
	v_add_f32_e32 v178, v178, v189
	v_add_f32_e32 v180, v180, v190
	v_add_f32_e32 v182, v182, v191
	ds_bpermute_b32 v188, v6, v176
	ds_bpermute_b32 v189, v6, v178
	ds_bpermute_b32 v190, v6, v180
	ds_bpermute_b32 v191, v6, v182
	s_waitcnt lgkmcnt(0)
	v_add_f32_e32 v176, v176, v188
	v_add_f32_e32 v178, v178, v189
	v_add_f32_e32 v180, v180, v190
	v_add_f32_e32 v182, v182, v191
	ds_bpermute_b32 v188, v7, v176
	ds_bpermute_b32 v189, v7, v178
	ds_bpermute_b32 v190, v7, v180
	ds_bpermute_b32 v191, v7, v182
	s_waitcnt lgkmcnt(0)
	v_add_f32_e32 v176, v176, v188
	v_add_f32_e32 v178, v178, v189
	v_add_f32_e32 v180, v180, v190
	v_add_f32_e32 v182, v182, v191
	v_fmamk_f32 v176, v176, 0x3a800000, v8
	v_fmamk_f32 v178, v178, 0x3a800000, v8
	v_fmamk_f32 v180, v180, 0x3a800000, v8
	v_fmamk_f32 v182, v182, 0x3a800000, v8
	v_rsq_f32_e32 v176, v176
	v_rsq_f32_e32 v178, v178
	v_rsq_f32_e32 v180, v180
	v_rsq_f32_e32 v182, v182
	s_nop 1
	v_pk_mul_f32 v[112:113], v[112:113], v[176:177] op_sel_hi:[1,0]
	v_pk_mul_f32 v[128:129], v[128:129], v[178:179] op_sel_hi:[1,0]
	v_pk_mul_f32 v[144:145], v[144:145], v[180:181] op_sel_hi:[1,0]
	v_pk_mul_f32 v[160:161], v[160:161], v[182:183] op_sel_hi:[1,0]
	v_pk_mul_f32 v[114:115], v[114:115], v[176:177] op_sel_hi:[1,0]
	v_pk_mul_f32 v[130:131], v[130:131], v[178:179] op_sel_hi:[1,0]
	v_pk_mul_f32 v[146:147], v[146:147], v[180:181] op_sel_hi:[1,0]
	v_pk_mul_f32 v[162:163], v[162:163], v[182:183] op_sel_hi:[1,0]
	v_pk_mul_f32 v[116:117], v[116:117], v[176:177] op_sel_hi:[1,0]
	v_pk_mul_f32 v[132:133], v[132:133], v[178:179] op_sel_hi:[1,0]
	v_pk_mul_f32 v[148:149], v[148:149], v[180:181] op_sel_hi:[1,0]
	v_pk_mul_f32 v[164:165], v[164:165], v[182:183] op_sel_hi:[1,0]
	v_pk_mul_f32 v[118:119], v[118:119], v[176:177] op_sel_hi:[1,0]
	v_pk_mul_f32 v[134:135], v[134:135], v[178:179] op_sel_hi:[1,0]
	v_pk_mul_f32 v[150:151], v[150:151], v[180:181] op_sel_hi:[1,0]
	v_pk_mul_f32 v[166:167], v[166:167], v[182:183] op_sel_hi:[1,0]
	v_pk_mul_f32 v[120:121], v[120:121], v[176:177] op_sel_hi:[1,0]
	v_pk_mul_f32 v[136:137], v[136:137], v[178:179] op_sel_hi:[1,0]
	v_pk_mul_f32 v[152:153], v[152:153], v[180:181] op_sel_hi:[1,0]
	v_pk_mul_f32 v[168:169], v[168:169], v[182:183] op_sel_hi:[1,0]
	v_pk_mul_f32 v[122:123], v[122:123], v[176:177] op_sel_hi:[1,0]
	v_pk_mul_f32 v[138:139], v[138:139], v[178:179] op_sel_hi:[1,0]
	v_pk_mul_f32 v[154:155], v[154:155], v[180:181] op_sel_hi:[1,0]
	v_pk_mul_f32 v[170:171], v[170:171], v[182:183] op_sel_hi:[1,0]
	v_pk_mul_f32 v[124:125], v[124:125], v[176:177] op_sel_hi:[1,0]
	v_pk_mul_f32 v[140:141], v[140:141], v[178:179] op_sel_hi:[1,0]
	v_pk_mul_f32 v[156:157], v[156:157], v[180:181] op_sel_hi:[1,0]
	v_pk_mul_f32 v[172:173], v[172:173], v[182:183] op_sel_hi:[1,0]
	v_pk_mul_f32 v[126:127], v[126:127], v[176:177] op_sel_hi:[1,0]
	v_pk_mul_f32 v[142:143], v[142:143], v[178:179] op_sel_hi:[1,0]
	v_pk_mul_f32 v[158:159], v[158:159], v[180:181] op_sel_hi:[1,0]
	v_pk_mul_f32 v[174:175], v[174:175], v[182:183] op_sel_hi:[1,0]
	v_pk_fma_f32 v[112:113], v[112:113], v[16:17], v[32:33]
	v_pk_fma_f32 v[128:129], v[128:129], v[16:17], v[32:33]
	v_pk_fma_f32 v[144:145], v[144:145], v[16:17], v[32:33]
	v_pk_fma_f32 v[160:161], v[160:161], v[16:17], v[32:33]
	v_pk_fma_f32 v[114:115], v[114:115], v[18:19], v[34:35]
	v_pk_fma_f32 v[130:131], v[130:131], v[18:19], v[34:35]
	v_pk_fma_f32 v[146:147], v[146:147], v[18:19], v[34:35]
	v_pk_fma_f32 v[162:163], v[162:163], v[18:19], v[34:35]
	v_pk_fma_f32 v[116:117], v[116:117], v[20:21], v[36:37]
	v_pk_fma_f32 v[132:133], v[132:133], v[20:21], v[36:37]
	v_pk_fma_f32 v[148:149], v[148:149], v[20:21], v[36:37]
	v_pk_fma_f32 v[164:165], v[164:165], v[20:21], v[36:37]
	v_pk_fma_f32 v[118:119], v[118:119], v[22:23], v[38:39]
	v_pk_fma_f32 v[134:135], v[134:135], v[22:23], v[38:39]
	v_pk_fma_f32 v[150:151], v[150:151], v[22:23], v[38:39]
	v_pk_fma_f32 v[166:167], v[166:167], v[22:23], v[38:39]
	v_pk_fma_f32 v[120:121], v[120:121], v[24:25], v[40:41]
	v_pk_fma_f32 v[136:137], v[136:137], v[24:25], v[40:41]
	v_pk_fma_f32 v[152:153], v[152:153], v[24:25], v[40:41]
	v_pk_fma_f32 v[168:169], v[168:169], v[24:25], v[40:41]
	v_pk_fma_f32 v[122:123], v[122:123], v[26:27], v[42:43]
	v_pk_fma_f32 v[138:139], v[138:139], v[26:27], v[42:43]
	v_pk_fma_f32 v[154:155], v[154:155], v[26:27], v[42:43]
	v_pk_fma_f32 v[170:171], v[170:171], v[26:27], v[42:43]
	v_pk_fma_f32 v[124:125], v[124:125], v[28:29], v[44:45]
	v_pk_fma_f32 v[140:141], v[140:141], v[28:29], v[44:45]
	v_pk_fma_f32 v[156:157], v[156:157], v[28:29], v[44:45]
	v_pk_fma_f32 v[172:173], v[172:173], v[28:29], v[44:45]
	v_pk_fma_f32 v[126:127], v[126:127], v[30:31], v[46:47]
	v_pk_fma_f32 v[142:143], v[142:143], v[30:31], v[46:47]
	v_pk_fma_f32 v[158:159], v[158:159], v[30:31], v[46:47]
	v_pk_fma_f32 v[174:175], v[174:175], v[30:31], v[46:47]
	s_mov_b32 s5, s0
	s_lshl_b32 s4, s5, 12
	s_add_u32 s2, s10, s4
	s_addc_u32 s3, s11, 0
	global_store_dwordx4 v1, v[112:115], s[2:3]
	global_store_dwordx4 v1, v[116:119], s[2:3] offset:16
	global_store_dwordx4 v1, v[120:123], s[2:3] offset:2048
	global_store_dwordx4 v1, v[124:127], s[2:3] offset:2064
	s_mov_b32 s4, s46
	s_add_i32 s5, s0, s4
	s_cmp_lt_i32 s5, 0x8000
	s_cbranch_scc0 .Llnf_ns1_1
	s_lshl_b32 s4, s5, 12
	s_add_u32 s2, s10, s4
	s_addc_u32 s3, s11, 0
	global_store_dwordx4 v1, v[128:131], s[2:3]
	global_store_dwordx4 v1, v[132:135], s[2:3] offset:16
	global_store_dwordx4 v1, v[136:139], s[2:3] offset:2048
	global_store_dwordx4 v1, v[140:143], s[2:3] offset:2064
.Llnf_ns1_1:
	s_mul_i32 s4, s46, 2
	s_add_i32 s5, s0, s4
	s_cmp_lt_i32 s5, 0x8000
	s_cbranch_scc0 .Llnf_ns1_2
	s_lshl_b32 s4, s5, 12
	s_add_u32 s2, s10, s4
	s_addc_u32 s3, s11, 0
	global_store_dwordx4 v1, v[144:147], s[2:3]
	global_store_dwordx4 v1, v[148:151], s[2:3] offset:16
	global_store_dwordx4 v1, v[152:155], s[2:3] offset:2048
	global_store_dwordx4 v1, v[156:159], s[2:3] offset:2064
.Llnf_ns1_2:
	s_mul_i32 s4, s46, 3
	s_add_i32 s5, s0, s4
	s_cmp_lt_i32 s5, 0x8000
	s_cbranch_scc0 .Llnf_ns1_3
	s_lshl_b32 s4, s5, 12
	s_add_u32 s2, s10, s4
	s_addc_u32 s3, s11, 0
	global_store_dwordx4 v1, v[160:163], s[2:3]
	global_store_dwordx4 v1, v[164:167], s[2:3] offset:16
	global_store_dwordx4 v1, v[168:171], s[2:3] offset:2048
	global_store_dwordx4 v1, v[172:175], s[2:3] offset:2064

.Llnf_top1:
	s_waitcnt vmcnt(16)
	v_lshlrev_b32_e32 v112, 16, v80
	v_and_b32_e32 v113, 0xffff0000, v80
	v_lshlrev_b32_e32 v128, 16, v88
	v_and_b32_e32 v129, 0xffff0000, v88
	v_lshlrev_b32_e32 v144, 16, v96
	v_and_b32_e32 v145, 0xffff0000, v96
	v_lshlrev_b32_e32 v160, 16, v104
	v_and_b32_e32 v161, 0xffff0000, v104
	v_lshlrev_b32_e32 v114, 16, v81
	v_and_b32_e32 v115, 0xffff0000, v81
	v_lshlrev_b32_e32 v130, 16, v89
	v_and_b32_e32 v131, 0xffff0000, v89
	v_lshlrev_b32_e32 v146, 16, v97
	v_and_b32_e32 v147, 0xffff0000, v97
	v_lshlrev_b32_e32 v162, 16, v105
	v_and_b32_e32 v163, 0xffff0000, v105
	v_lshlrev_b32_e32 v116, 16, v82
	v_and_b32_e32 v117, 0xffff0000, v82
	v_lshlrev_b32_e32 v132, 16, v90
	v_and_b32_e32 v133, 0xffff0000, v90
	v_lshlrev_b32_e32 v148, 16, v98
	v_and_b32_e32 v149, 0xffff0000, v98
	v_lshlrev_b32_e32 v164, 16, v106
	v_and_b32_e32 v165, 0xffff0000, v106
	v_lshlrev_b32_e32 v118, 16, v83
	v_and_b32_e32 v119, 0xffff0000, v83
	v_lshlrev_b32_e32 v134, 16, v91
	v_and_b32_e32 v135, 0xffff0000, v91
	v_lshlrev_b32_e32 v150, 16, v99
	v_and_b32_e32 v151, 0xffff0000, v99
	v_lshlrev_b32_e32 v166, 16, v107
	v_and_b32_e32 v167, 0xffff0000, v107
	v_lshlrev_b32_e32 v120, 16, v84
	v_and_b32_e32 v121, 0xffff0000, v84
	v_lshlrev_b32_e32 v136, 16, v92
	v_and_b32_e32 v137, 0xffff0000, v92
	v_lshlrev_b32_e32 v152, 16, v100
	v_and_b32_e32 v153, 0xffff0000, v100
	v_lshlrev_b32_e32 v168, 16, v108
	v_and_b32_e32 v169, 0xffff0000, v108
	v_lshlrev_b32_e32 v122, 16, v85
	v_and_b32_e32 v123, 0xffff0000, v85
	v_lshlrev_b32_e32 v138, 16, v93
	v_and_b32_e32 v139, 0xffff0000, v93
	v_lshlrev_b32_e32 v154, 16, v101
	v_and_b32_e32 v155, 0xffff0000, v101
	v_lshlrev_b32_e32 v170, 16, v109
	v_and_b32_e32 v171, 0xffff0000, v109
	v_lshlrev_b32_e32 v124, 16, v86
	v_and_b32_e32 v125, 0xffff0000, v86
	v_lshlrev_b32_e32 v140, 16, v94
	v_and_b32_e32 v141, 0xffff0000, v94
	v_lshlrev_b32_e32 v156, 16, v102
	v_and_b32_e32 v157, 0xffff0000, v102
	v_lshlrev_b32_e32 v172, 16, v110
	v_and_b32_e32 v173, 0xffff0000, v110
	v_lshlrev_b32_e32 v126, 16, v87
	v_and_b32_e32 v127, 0xffff0000, v87
	v_lshlrev_b32_e32 v142, 16, v95
	v_and_b32_e32 v143, 0xffff0000, v95
	v_lshlrev_b32_e32 v158, 16, v103
	v_and_b32_e32 v159, 0xffff0000, v103
	v_lshlrev_b32_e32 v174, 16, v111
	v_and_b32_e32 v175, 0xffff0000, v111
	v_add_f32_e32 v176, v112, v113
	v_add_f32_e32 v178, v128, v129
	v_add_f32_e32 v180, v144, v145
	v_add_f32_e32 v182, v160, v161
	v_add_f32_e32 v176, v176, v114
	v_add_f32_e32 v178, v178, v130
	v_add_f32_e32 v180, v180, v146
	v_add_f32_e32 v182, v182, v162
	v_add_f32_e32 v176, v176, v115
	v_add_f32_e32 v178, v178, v131
	v_add_f32_e32 v180, v180, v147
	v_add_f32_e32 v182, v182, v163
	v_add_f32_e32 v176, v176, v116
	v_add_f32_e32 v178, v178, v132
	v_add_f32_e32 v180, v180, v148
	v_add_f32_e32 v182, v182, v164
	v_add_f32_e32 v176, v176, v117
	v_add_f32_e32 v178, v178, v133
	v_add_f32_e32 v180, v180, v149
	v_add_f32_e32 v182, v182, v165
	v_add_f32_e32 v176, v176, v118
	v_add_f32_e32 v178, v178, v134
	v_add_f32_e32 v180, v180, v150
	v_add_f32_e32 v182, v182, v166
	v_add_f32_e32 v176, v176, v119
	v_add_f32_e32 v178, v178, v135
	v_add_f32_e32 v180, v180, v151
	v_add_f32_e32 v182, v182, v167
	v_add_f32_e32 v176, v176, v120
	v_add_f32_e32 v178, v178, v136
	v_add_f32_e32 v180, v180, v152
	v_add_f32_e32 v182, v182, v168
	v_add_f32_e32 v176, v176, v121
	v_add_f32_e32 v178, v178, v137
	v_add_f32_e32 v180, v180, v153
	v_add_f32_e32 v182, v182, v169
	v_add_f32_e32 v176, v176, v122
	v_add_f32_e32 v178, v178, v138
	v_add_f32_e32 v180, v180, v154
	v_add_f32_e32 v182, v182, v170
	v_add_f32_e32 v176, v176, v123
	v_add_f32_e32 v178, v178, v139
	v_add_f32_e32 v180, v180, v155
	v_add_f32_e32 v182, v182, v171
	v_add_f32_e32 v176, v176, v124
	v_add_f32_e32 v178, v178, v140
	v_add_f32_e32 v180, v180, v156
	v_add_f32_e32 v182, v182, v172
	v_add_f32_e32 v176, v176, v125
	v_add_f32_e32 v178, v178, v141
	v_add_f32_e32 v180, v180, v157
	v_add_f32_e32 v182, v182, v173
	v_add_f32_e32 v176, v176, v126
	v_add_f32_e32 v178, v178, v142
	v_add_f32_e32 v180, v180, v158
	v_add_f32_e32 v182, v182, v174
	v_add_f32_e32 v176, v176, v127
	v_add_f32_e32 v178, v178, v143
	v_add_f32_e32 v180, v180, v159
	v_add_f32_e32 v182, v182, v175
	s_add_i32 s1, s0, s14
	s_cmp_lt_i32 s1, 0x8000
	s_cbranch_scc0 .Llnf_np2
	s_mov_b32 s5, s1
	s_lshl_b32 s4, s5, 11
	s_add_u32 s2, s62, s4
	s_addc_u32 s3, s63, 0
	global_load_dwordx4 v[48:51], v0, s[2:3] nt
	global_load_dwordx4 v[52:55], v0, s[2:3] offset:1024 nt
	s_mov_b32 s4, s46
	s_add_i32 s5, s1, s4
	s_cmp_lt_i32 s5, 0x8000
	s_cselect_b32 s5, s5, s1
	s_lshl_b32 s4, s5, 11
	s_add_u32 s2, s62, s4
	s_addc_u32 s3, s63, 0
	global_load_dwordx4 v[56:59], v0, s[2:3] nt
	global_load_dwordx4 v[60:63], v0, s[2:3] offset:1024 nt
	s_mul_i32 s4, s46, 2
	s_add_i32 s5, s1, s4
	s_cmp_lt_i32 s5, 0x8000
	s_cselect_b32 s5, s5, s1
	s_lshl_b32 s4, s5, 11
	s_add_u32 s2, s62, s4
	s_addc_u32 s3, s63, 0
	global_load_dwordx4 v[64:67], v0, s[2:3] nt
	global_load_dwordx4 v[68:71], v0, s[2:3] offset:1024 nt
	s_mul_i32 s4, s46, 3
	s_add_i32 s5, s1, s4
	s_cmp_lt_i32 s5, 0x8000
	s_cselect_b32 s5, s5, s1
	s_lshl_b32 s4, s5, 11
	s_add_u32 s2, s62, s4
	s_addc_u32 s3, s63, 0
	global_load_dwordx4 v[72:75], v0, s[2:3] nt
	global_load_dwordx4 v[76:79], v0, s[2:3] offset:1024 nt

.Llnf_ns2_3:
	s_nop 1
	s_mov_b32 s0, s1
	s_cmp_lt_i32 s0, 0x8000
	s_cbranch_scc0 .Llnf_done
	s_waitcnt vmcnt(16)
	v_lshlrev_b32_e32 v112, 16, v48
	v_and_b32_e32 v113, 0xffff0000, v48
	v_lshlrev_b32_e32 v128, 16, v56
	v_and_b32_e32 v129, 0xffff0000, v56
	v_lshlrev_b32_e32 v144, 16, v64
	v_and_b32_e32 v145, 0xffff0000, v64
	v_lshlrev_b32_e32 v160, 16, v72
	v_and_b32_e32 v161, 0xffff0000, v72
	v_lshlrev_b32_e32 v114, 16, v49
	v_and_b32_e32 v115, 0xffff0000, v49
	v_lshlrev_b32_e32 v130, 16, v57
	v_and_b32_e32 v131, 0xffff0000, v57
	v_lshlrev_b32_e32 v146, 16, v65
	v_and_b32_e32 v147, 0xffff0000, v65
	v_lshlrev_b32_e32 v162, 16, v73
	v_and_b32_e32 v163, 0xffff0000, v73
	v_lshlrev_b32_e32 v116, 16, v50
	v_and_b32_e32 v117, 0xffff0000, v50
	v_lshlrev_b32_e32 v132, 16, v58
	v_and_b32_e32 v133, 0xffff0000, v58
	v_lshlrev_b32_e32 v148, 16, v66
	v_and_b32_e32 v149, 0xffff0000, v66
	v_lshlrev_b32_e32 v164, 16, v74
	v_and_b32_e32 v165, 0xffff0000, v74
	v_lshlrev_b32_e32 v118, 16, v51
	v_and_b32_e32 v119, 0xffff0000, v51
	v_lshlrev_b32_e32 v134, 16, v59
	v_and_b32_e32 v135, 0xffff0000, v59
	v_lshlrev_b32_e32 v150, 16, v67
	v_and_b32_e32 v151, 0xffff0000, v67
	v_lshlrev_b32_e32 v166, 16, v75
	v_and_b32_e32 v167, 0xffff0000, v75
	v_lshlrev_b32_e32 v120, 16, v52
	v_and_b32_e32 v121, 0xffff0000, v52
	v_lshlrev_b32_e32 v136, 16, v60
	v_and_b32_e32 v137, 0xffff0000, v60
	v_lshlrev_b32_e32 v152, 16, v68
	v_and_b32_e32 v153, 0xffff0000, v68
	v_lshlrev_b32_e32 v168, 16, v76
	v_and_b32_e32 v169, 0xffff0000, v76
	v_lshlrev_b32_e32 v122, 16, v53
	v_and_b32_e32 v123, 0xffff0000, v53
	v_lshlrev_b32_e32 v138, 16, v61
	v_and_b32_e32 v139, 0xffff0000, v61
	v_lshlrev_b32_e32 v154, 16, v69
	v_and_b32_e32 v155, 0xffff0000, v69
	v_lshlrev_b32_e32 v170, 16, v77
	v_and_b32_e32 v171, 0xffff0000, v77
	v_lshlrev_b32_e32 v124, 16, v54
	v_and_b32_e32 v125, 0xffff0000, v54
	v_lshlrev_b32_e32 v140, 16, v62
	v_and_b32_e32 v141, 0xffff0000, v62
	v_lshlrev_b32_e32 v156, 16, v70
	v_and_b32_e32 v157, 0xffff0000, v70
	v_lshlrev_b32_e32 v172, 16, v78
	v_and_b32_e32 v173, 0xffff0000, v78
	v_lshlrev_b32_e32 v126, 16, v55
	v_and_b32_e32 v127, 0xffff0000, v55
	v_lshlrev_b32_e32 v142, 16, v63
	v_and_b32_e32 v143, 0xffff0000, v63
	v_lshlrev_b32_e32 v158, 16, v71
	v_and_b32_e32 v159, 0xffff0000, v71
	v_lshlrev_b32_e32 v174, 16, v79
	v_and_b32_e32 v175, 0xffff0000, v79
	v_add_f32_e32 v176, v112, v113
	v_add_f32_e32 v178, v128, v129
	v_add_f32_e32 v180, v144, v145
	v_add_f32_e32 v182, v160, v161
	v_add_f32_e32 v176, v176, v114
	v_add_f32_e32 v178, v178, v130
	v_add_f32_e32 v180, v180, v146
	v_add_f32_e32 v182, v182, v162
	v_add_f32_e32 v176, v176, v115
	v_add_f32_e32 v178, v178, v131
	v_add_f32_e32 v180, v180, v147
	v_add_f32_e32 v182, v182, v163
	v_add_f32_e32 v176, v176, v116
	v_add_f32_e32 v178, v178, v132
	v_add_f32_e32 v180, v180, v148
	v_add_f32_e32 v182, v182, v164
	v_add_f32_e32 v176, v176, v117
	v_add_f32_e32 v178, v178, v133
	v_add_f32_e32 v180, v180, v149
	v_add_f32_e32 v182, v182, v165
	v_add_f32_e32 v176, v176, v118
	v_add_f32_e32 v178, v178, v134
	v_add_f32_e32 v180, v180, v150
	v_add_f32_e32 v182, v182, v166
	v_add_f32_e32 v176, v176, v119
	v_add_f32_e32 v178, v178, v135
	v_add_f32_e32 v180, v180, v151
	v_add_f32_e32 v182, v182, v167
	v_add_f32_e32 v176, v176, v120
	v_add_f32_e32 v178, v178, v136
	v_add_f32_e32 v180, v180, v152
	v_add_f32_e32 v182, v182, v168
	v_add_f32_e32 v176, v176, v121
	v_add_f32_e32 v178, v178, v137
	v_add_f32_e32 v180, v180, v153
	v_add_f32_e32 v182, v182, v169
	v_add_f32_e32 v176, v176, v122
	v_add_f32_e32 v178, v178, v138
	v_add_f32_e32 v180, v180, v154
	v_add_f32_e32 v182, v182, v170
	v_add_f32_e32 v176, v176, v123
	v_add_f32_e32 v178, v178, v139
	v_add_f32_e32 v180, v180, v155
	v_add_f32_e32 v182, v182, v171
	v_add_f32_e32 v176, v176, v124
	v_add_f32_e32 v178, v178, v140
	v_add_f32_e32 v180, v180, v156
	v_add_f32_e32 v182, v182, v172
	v_add_f32_e32 v176, v176, v125
	v_add_f32_e32 v178, v178, v141
	v_add_f32_e32 v180, v180, v157
	v_add_f32_e32 v182, v182, v173
	v_add_f32_e32 v176, v176, v126
	v_add_f32_e32 v178, v178, v142
	v_add_f32_e32 v180, v180, v158
	v_add_f32_e32 v182, v182, v174
	v_add_f32_e32 v176, v176, v127
	v_add_f32_e32 v178, v178, v143
	v_add_f32_e32 v180, v180, v159
	v_add_f32_e32 v182, v182, v175
	s_add_i32 s1, s0, s14
	s_cmp_lt_i32 s1, 0x8000
	s_cbranch_scc0 .Llnf_np3
	s_mov_b32 s5, s1
	s_lshl_b32 s4, s5, 11
	s_add_u32 s2, s62, s4
	s_addc_u32 s3, s63, 0
	global_load_dwordx4 v[80:83], v0, s[2:3] nt
	global_load_dwordx4 v[84:87], v0, s[2:3] offset:1024 nt
	s_mov_b32 s4, s46
	s_add_i32 s5, s1, s4
	s_cmp_lt_i32 s5, 0x8000
	s_cselect_b32 s5, s5, s1
	s_lshl_b32 s4, s5, 11
	s_add_u32 s2, s62, s4
	s_addc_u32 s3, s63, 0
	global_load_dwordx4 v[88:91], v0, s[2:3] nt
	global_load_dwordx4 v[92:95], v0, s[2:3] offset:1024 nt
	s_mul_i32 s4, s46, 2
	s_add_i32 s5, s1, s4
	s_cmp_lt_i32 s5, 0x8000
	s_cselect_b32 s5, s5, s1
	s_lshl_b32 s4, s5, 11
	s_add_u32 s2, s62, s4
	s_addc_u32 s3, s63, 0
	global_load_dwordx4 v[96:99], v0, s[2:3] nt
	global_load_dwordx4 v[100:103], v0, s[2:3] offset:1024 nt
	s_mul_i32 s4, s46, 3
	s_add_i32 s5, s1, s4
	s_cmp_lt_i32 s5, 0x8000
	s_cselect_b32 s5, s5, s1
	s_lshl_b32 s4, s5, 11
	s_add_u32 s2, s62, s4
	s_addc_u32 s3, s63, 0
	global_load_dwordx4 v[104:107], v0, s[2:3] nt
	global_load_dwordx4 v[108:111], v0, s[2:3] offset:1024 nt

.Llnf_done:
.LBB0_681:
	s_endpgm
